# double-buffered tail transposer: layer-1 ffn_down + Mamba out-proj weights converted by idle WGs in phase 7 tail, layer-1 PLE gate/proj weights in phase 19 tail
# speedup vs baseline: 1.0144x; 1.0076x over previous
; #define LAS __attribute__((address_space(3)))
; __device__ __forceinline__ unsigned cvt_pk_bf16(float lo, float hi) { unsigned r; asm volatile("v_cvt_pk_bf16_f32 %0, %1, %2" : "=v"(r) : "v"(lo), "v"(hi)); return r; }
; __device__ __forceinline__ void xpose_item(const float* src, int ld, bf16_t* dst, int K, int k0, LAS float* scr, int lane, const float* gk) {
;     if (src) {
; #pragma unroll 8
;         for (int i = 0; i < 32; ++i) { const int kk = 2 * i + (lane >> 5); scr[kk * 33 + (lane & 31)] = __builtin_nontemporal_load(src + (size_t)(k0 + kk) * ld + (lane & 31)); }
;     } else {
; #pragma unroll 8
;         for (int i = 0; i < 32; ++i) { const int kk = 2 * i + (lane >> 5); scr[kk * 33 + (lane & 31)] = 0.f; }
;     }
;     const int c = lane & 7;
;     f32x4 g0 = (f32x4){1.f, 1.f, 1.f, 1.f}, g1 = g0;
;     if (gk) { g0 = *(const f32x4*)(gk + k0 + 8 * c); g1 = *(const f32x4*)(gk + k0 + 8 * c + 4); }
;     asm volatile("s_waitcnt lgkmcnt(0)" ::: "memory");
; #pragma unroll
;     for (int j = 0; j < 4; ++j) { const int n = (lane >> 3) + 8 * j; const LAS float* s = scr + (8 * c) * 33 + n;
;         u32x4 o; o.x = cvt_pk_bf16(s[0 * 33] * g0[0], s[1 * 33] * g0[1]); o.y = cvt_pk_bf16(s[2 * 33] * g0[2], s[3 * 33] * g0[3]); o.z = cvt_pk_bf16(s[4 * 33] * g1[0], s[5 * 33] * g1[1]); o.w = cvt_pk_bf16(s[6 * 33] * g1[2], s[7 * 33] * g1[3]);
;         *(u32x4*)(dst + (size_t)n * K + k0 + 8 * c) = o; }
;     asm volatile("s_waitcnt lgkmcnt(0)" ::: "memory");
; }
; __global__ void __launch_bounds__(512) mega(Args a_byval) {
;     ...
;             it = xpose_all(a.in[25] + (size_t)lyr * D * DFF, nullptr, 2048, DFF, 2048, 2048, 0, (bf16_t*)(ws + (lyr ? WS_W_D : WS_W_D0)), it, NGW, scr, lane);
.LBB0_418:
	s_waitcnt vmcnt(0)
	s_barrier
	s_cmp_lg_u32 s76, 7
	s_cbranch_scc1 .Lxt7_done
	v_readlane_b32 s59, v255, 5
	s_cmpk_lg_i32 s59, 0x100
	s_cbranch_scc1 .Lxt7_done
	s_cmpk_lt_i32 s94, 0x80
	s_cbranch_scc1 .Lxt7_done
	s_sub_i32 s59, s94, 0x80
	s_lshl_b32 s59, s59, 3
	s_add_i32 s59, s59, s95
	s_mul_i32 s64, s95, 0x2100
	v_and_b32_e32 v2, 31, v200
	v_lshrrev_b32_e32 v3, 5, v200
	v_lshlrev_b32_e32 v4, 2, v2
	v_lshl_add_u32 v5, v3, 13, v4
	v_mul_u32_u24_e32 v6, 0x84, v3
	v_add3_u32 v6, v6, v4, s64
	v_and_b32_e32 v7, 7, v200
	v_lshrrev_b32_e32 v8, 3, v200
	v_mul_u32_u24_e32 v9, 0x420, v7
	v_lshl_add_u32 v9, v8, 2, v9
	v_add_u32_e32 v9, s64, v9
	s_cmpk_ge_i32 s59, 0x1600
	s_cbranch_scc1 .Lxpfd_end
	s_load_dwordx2 s[60:61], s[92:93], 0xc8
	s_load_dwordx2 s[62:63], s[92:93], 0xe8
	v_mov_b32_e32 v10, 0x2c00
	v_mul_u32_u24_e32 v10, v8, v10
	v_lshl_add_u32 v12, v7, 4, v10
	v_add_u32_e32 v13, 0x16000, v12
	v_add_u32_e32 v14, 0x2c000, v12
	v_add_u32_e32 v15, 0x42000, v12
	s_waitcnt lgkmcnt(0)
	s_add_u32 s60, s60, 0x2c00000
	s_addc_u32 s61, s61, 0
	s_add_u32 s62, s62, 0x6500000
	s_addc_u32 s63, s63, 0
	s_lshr_b32 s64, s59, 6
	s_and_b32 s65, s59, 63
	s_lshl_b32 s66, s64, 19
	s_lshl_b32 s67, s65, 7
	s_add_i32 s66, s66, s67
	s_add_u32 s66, s60, s66
	s_addc_u32 s67, s61, 0
	v_mov_b32_e32 v11, v5
	global_load_dword v20, v11, s[66:67] nt
	v_add_u32_e32 v11, 0x4000, v11
	global_load_dword v21, v11, s[66:67] nt
	v_add_u32_e32 v11, 0x4000, v11
	global_load_dword v22, v11, s[66:67] nt
	v_add_u32_e32 v11, 0x4000, v11
	global_load_dword v23, v11, s[66:67] nt
	v_add_u32_e32 v11, 0x4000, v11
	global_load_dword v24, v11, s[66:67] nt
	v_add_u32_e32 v11, 0x4000, v11
	global_load_dword v25, v11, s[66:67] nt
	v_add_u32_e32 v11, 0x4000, v11
	global_load_dword v26, v11, s[66:67] nt
	v_add_u32_e32 v11, 0x4000, v11
	global_load_dword v27, v11, s[66:67] nt
	v_add_u32_e32 v11, 0x4000, v11
	global_load_dword v28, v11, s[66:67] nt
	v_add_u32_e32 v11, 0x4000, v11
	global_load_dword v29, v11, s[66:67] nt
	v_add_u32_e32 v11, 0x4000, v11
	global_load_dword v30, v11, s[66:67] nt
	v_add_u32_e32 v11, 0x4000, v11
	global_load_dword v31, v11, s[66:67] nt
	v_add_u32_e32 v11, 0x4000, v11
	global_load_dword v32, v11, s[66:67] nt
	v_add_u32_e32 v11, 0x4000, v11
	global_load_dword v33, v11, s[66:67] nt
	v_add_u32_e32 v11, 0x4000, v11
	global_load_dword v34, v11, s[66:67] nt
	v_add_u32_e32 v11, 0x4000, v11
	global_load_dword v35, v11, s[66:67] nt
	v_add_u32_e32 v11, 0x4000, v11
	global_load_dword v36, v11, s[66:67] nt
	v_add_u32_e32 v11, 0x4000, v11
	global_load_dword v37, v11, s[66:67] nt
	v_add_u32_e32 v11, 0x4000, v11
	global_load_dword v38, v11, s[66:67] nt
	v_add_u32_e32 v11, 0x4000, v11
	global_load_dword v39, v11, s[66:67] nt
	v_add_u32_e32 v11, 0x4000, v11
	global_load_dword v40, v11, s[66:67] nt
	v_add_u32_e32 v11, 0x4000, v11
	global_load_dword v41, v11, s[66:67] nt
	v_add_u32_e32 v11, 0x4000, v11
	global_load_dword v42, v11, s[66:67] nt
	v_add_u32_e32 v11, 0x4000, v11
	global_load_dword v43, v11, s[66:67] nt
	v_add_u32_e32 v11, 0x4000, v11
	global_load_dword v44, v11, s[66:67] nt
	v_add_u32_e32 v11, 0x4000, v11
	global_load_dword v45, v11, s[66:67] nt
	v_add_u32_e32 v11, 0x4000, v11
	global_load_dword v46, v11, s[66:67] nt
	v_add_u32_e32 v11, 0x4000, v11
	global_load_dword v47, v11, s[66:67] nt
	v_add_u32_e32 v11, 0x4000, v11
	global_load_dword v48, v11, s[66:67] nt
	v_add_u32_e32 v11, 0x4000, v11
	global_load_dword v49, v11, s[66:67] nt
	v_add_u32_e32 v11, 0x4000, v11
	global_load_dword v50, v11, s[66:67] nt
	v_add_u32_e32 v11, 0x4000, v11
	global_load_dword v51, v11, s[66:67] nt
.Lxpfd_loop:
	s_add_i32 s32, s59, 0x400
	s_cmpk_lt_i32 s32, 0x1600
	s_cbranch_scc0 .Lxpfd_dumB
	s_lshr_b32 s64, s32, 6
	s_and_b32 s65, s32, 63
	s_lshl_b32 s66, s64, 19
	s_lshl_b32 s67, s65, 7
	s_add_i32 s66, s66, s67
	s_add_u32 s66, s60, s66
	s_addc_u32 s67, s61, 0
	v_mov_b32_e32 v11, v5
	global_load_dword v108, v11, s[66:67] nt
	v_add_u32_e32 v11, 0x4000, v11
	global_load_dword v109, v11, s[66:67] nt
	v_add_u32_e32 v11, 0x4000, v11
	global_load_dword v110, v11, s[66:67] nt
	v_add_u32_e32 v11, 0x4000, v11
	global_load_dword v111, v11, s[66:67] nt
	v_add_u32_e32 v11, 0x4000, v11
	global_load_dword v112, v11, s[66:67] nt
	v_add_u32_e32 v11, 0x4000, v11
	global_load_dword v113, v11, s[66:67] nt
	v_add_u32_e32 v11, 0x4000, v11
	global_load_dword v114, v11, s[66:67] nt
	v_add_u32_e32 v11, 0x4000, v11
	global_load_dword v115, v11, s[66:67] nt
	v_add_u32_e32 v11, 0x4000, v11
	global_load_dword v116, v11, s[66:67] nt
	v_add_u32_e32 v11, 0x4000, v11
	global_load_dword v117, v11, s[66:67] nt
	v_add_u32_e32 v11, 0x4000, v11
	global_load_dword v118, v11, s[66:67] nt
	v_add_u32_e32 v11, 0x4000, v11
	global_load_dword v119, v11, s[66:67] nt
	v_add_u32_e32 v11, 0x4000, v11
	global_load_dword v120, v11, s[66:67] nt
	v_add_u32_e32 v11, 0x4000, v11
	global_load_dword v121, v11, s[66:67] nt
	v_add_u32_e32 v11, 0x4000, v11
	global_load_dword v122, v11, s[66:67] nt
	v_add_u32_e32 v11, 0x4000, v11
	global_load_dword v123, v11, s[66:67] nt
	v_add_u32_e32 v11, 0x4000, v11
	global_load_dword v124, v11, s[66:67] nt
	v_add_u32_e32 v11, 0x4000, v11
	global_load_dword v125, v11, s[66:67] nt
	v_add_u32_e32 v11, 0x4000, v11
	global_load_dword v126, v11, s[66:67] nt
	v_add_u32_e32 v11, 0x4000, v11
	global_load_dword v127, v11, s[66:67] nt
	v_add_u32_e32 v11, 0x4000, v11
	global_load_dword v128, v11, s[66:67] nt
	v_add_u32_e32 v11, 0x4000, v11
	global_load_dword v129, v11, s[66:67] nt
	v_add_u32_e32 v11, 0x4000, v11
	global_load_dword v130, v11, s[66:67] nt
	v_add_u32_e32 v11, 0x4000, v11
	global_load_dword v131, v11, s[66:67] nt
	v_add_u32_e32 v11, 0x4000, v11
	global_load_dword v132, v11, s[66:67] nt
	v_add_u32_e32 v11, 0x4000, v11
	global_load_dword v133, v11, s[66:67] nt
	v_add_u32_e32 v11, 0x4000, v11
	global_load_dword v134, v11, s[66:67] nt
	v_add_u32_e32 v11, 0x4000, v11
	global_load_dword v135, v11, s[66:67] nt
	v_add_u32_e32 v11, 0x4000, v11
	global_load_dword v136, v11, s[66:67] nt
	v_add_u32_e32 v11, 0x4000, v11
	global_load_dword v137, v11, s[66:67] nt
	v_add_u32_e32 v11, 0x4000, v11
	global_load_dword v138, v11, s[66:67] nt
	v_add_u32_e32 v11, 0x4000, v11
	global_load_dword v139, v11, s[66:67] nt
	s_branch .Lxpfd_procA
; #define LAS __attribute__((address_space(3)))
; __device__ __forceinline__ unsigned cvt_pk_bf16(float lo, float hi) { unsigned r; asm volatile("v_cvt_pk_bf16_f32 %0, %1, %2" : "=v"(r) : "v"(lo), "v"(hi)); return r; }
; __device__ __forceinline__ void xpose_item(const float* src, int ld, bf16_t* dst, int K, int k0, LAS float* scr, int lane, const float* gk) {
;     if (src) {
; #pragma unroll 8
;         for (int i = 0; i < 32; ++i) { const int kk = 2 * i + (lane >> 5); scr[kk * 33 + (lane & 31)] = __builtin_nontemporal_load(src + (size_t)(k0 + kk) * ld + (lane & 31)); }
;     } else {
; #pragma unroll 8
;         for (int i = 0; i < 32; ++i) { const int kk = 2 * i + (lane >> 5); scr[kk * 33 + (lane & 31)] = 0.f; }
;     }
;     const int c = lane & 7;
;     f32x4 g0 = (f32x4){1.f, 1.f, 1.f, 1.f}, g1 = g0;
;     if (gk) { g0 = *(const f32x4*)(gk + k0 + 8 * c); g1 = *(const f32x4*)(gk + k0 + 8 * c + 4); }
;     asm volatile("s_waitcnt lgkmcnt(0)" ::: "memory");
; #pragma unroll
;     for (int j = 0; j < 4; ++j) { const int n = (lane >> 3) + 8 * j; const LAS float* s = scr + (8 * c) * 33 + n;
;         u32x4 o; o.x = cvt_pk_bf16(s[0 * 33] * g0[0], s[1 * 33] * g0[1]); o.y = cvt_pk_bf16(s[2 * 33] * g0[2], s[3 * 33] * g0[3]); o.z = cvt_pk_bf16(s[4 * 33] * g1[0], s[5 * 33] * g1[1]); o.w = cvt_pk_bf16(s[6 * 33] * g1[2], s[7 * 33] * g1[3]);
;         *(u32x4*)(dst + (size_t)n * K + k0 + 8 * c) = o; }
;     asm volatile("s_waitcnt lgkmcnt(0)" ::: "memory");
; }
; __global__ void __launch_bounds__(512) mega(Args a_byval) {
;     ...
;             it = xpose_all(a.in[25] + (size_t)lyr * D * DFF, nullptr, 2048, DFF, 2048, 2048, 0, (bf16_t*)(ws + (lyr ? WS_W_D : WS_W_D0)), it, NGW, scr, lane);
.Lxpfd_dumB:
	global_load_dword v108, v0, s[60:61]
	global_load_dword v109, v0, s[60:61]
	global_load_dword v110, v0, s[60:61]
	global_load_dword v111, v0, s[60:61]
	global_load_dword v112, v0, s[60:61]
	global_load_dword v113, v0, s[60:61]
	global_load_dword v114, v0, s[60:61]
	global_load_dword v115, v0, s[60:61]
	global_load_dword v116, v0, s[60:61]
	global_load_dword v117, v0, s[60:61]
	global_load_dword v118, v0, s[60:61]
	global_load_dword v119, v0, s[60:61]
	global_load_dword v120, v0, s[60:61]
	global_load_dword v121, v0, s[60:61]
	global_load_dword v122, v0, s[60:61]
	global_load_dword v123, v0, s[60:61]
	global_load_dword v124, v0, s[60:61]
	global_load_dword v125, v0, s[60:61]
	global_load_dword v126, v0, s[60:61]
	global_load_dword v127, v0, s[60:61]
	global_load_dword v128, v0, s[60:61]
	global_load_dword v129, v0, s[60:61]
	global_load_dword v130, v0, s[60:61]
	global_load_dword v131, v0, s[60:61]
	global_load_dword v132, v0, s[60:61]
	global_load_dword v133, v0, s[60:61]
	global_load_dword v134, v0, s[60:61]
	global_load_dword v135, v0, s[60:61]
	global_load_dword v136, v0, s[60:61]
	global_load_dword v137, v0, s[60:61]
	global_load_dword v138, v0, s[60:61]
	global_load_dword v139, v0, s[60:61]
.Lxpfd_procA:
	s_lshr_b32 s64, s59, 6
	s_and_b32 s65, s59, 63
	s_mul_i32 s68, s65, 0x58000
	s_lshl_b32 s64, s64, 7
	s_add_i32 s68, s68, s64
	s_add_u32 s64, s62, s68
	s_addc_u32 s65, s63, 0
	s_waitcnt vmcnt(63)
	ds_write_b32 v6, v20 offset:0
	s_waitcnt vmcnt(62)
	ds_write_b32 v6, v21 offset:264
	s_waitcnt vmcnt(61)
	ds_write_b32 v6, v22 offset:528
	s_waitcnt vmcnt(60)
	ds_write_b32 v6, v23 offset:792
	s_waitcnt vmcnt(59)
	ds_write_b32 v6, v24 offset:1056
	s_waitcnt vmcnt(58)
	ds_write_b32 v6, v25 offset:1320
	s_waitcnt vmcnt(57)
	ds_write_b32 v6, v26 offset:1584
	s_waitcnt vmcnt(56)
	ds_write_b32 v6, v27 offset:1848
	s_waitcnt vmcnt(55)
	ds_write_b32 v6, v28 offset:2112
	s_waitcnt vmcnt(54)
	ds_write_b32 v6, v29 offset:2376
	s_waitcnt vmcnt(53)
	ds_write_b32 v6, v30 offset:2640
	s_waitcnt vmcnt(52)
	ds_write_b32 v6, v31 offset:2904
	s_waitcnt vmcnt(51)
	ds_write_b32 v6, v32 offset:3168
	s_waitcnt vmcnt(50)
	ds_write_b32 v6, v33 offset:3432
	s_waitcnt vmcnt(49)
	ds_write_b32 v6, v34 offset:3696
	s_waitcnt vmcnt(48)
	ds_write_b32 v6, v35 offset:3960
	s_waitcnt vmcnt(47)
	ds_write_b32 v6, v36 offset:4224
	s_waitcnt vmcnt(46)
	ds_write_b32 v6, v37 offset:4488
	s_waitcnt vmcnt(45)
	ds_write_b32 v6, v38 offset:4752
	s_waitcnt vmcnt(44)
	ds_write_b32 v6, v39 offset:5016
	s_waitcnt vmcnt(43)
	ds_write_b32 v6, v40 offset:5280
	s_waitcnt vmcnt(42)
	ds_write_b32 v6, v41 offset:5544
	s_waitcnt vmcnt(41)
	ds_write_b32 v6, v42 offset:5808
	s_waitcnt vmcnt(40)
	ds_write_b32 v6, v43 offset:6072
	s_waitcnt vmcnt(39)
	ds_write_b32 v6, v44 offset:6336
	s_waitcnt vmcnt(38)
	ds_write_b32 v6, v45 offset:6600
	s_waitcnt vmcnt(37)
	ds_write_b32 v6, v46 offset:6864
	s_waitcnt vmcnt(36)
	ds_write_b32 v6, v47 offset:7128
	s_waitcnt vmcnt(35)
	ds_write_b32 v6, v48 offset:7392
	s_waitcnt vmcnt(34)
	ds_write_b32 v6, v49 offset:7656
	s_waitcnt vmcnt(33)
	ds_write_b32 v6, v50 offset:7920
	s_waitcnt vmcnt(32)
	ds_write_b32 v6, v51 offset:8184
	s_waitcnt lgkmcnt(0)
	ds_read2_b32 v[60:61], v9 offset0:0 offset1:33
	ds_read2_b32 v[62:63], v9 offset0:66 offset1:99
	ds_read2_b32 v[64:65], v9 offset0:132 offset1:165
	ds_read2_b32 v[66:67], v9 offset0:198 offset1:231
	ds_read2_b32 v[68:69], v9 offset0:8 offset1:41
	ds_read2_b32 v[70:71], v9 offset0:74 offset1:107
	ds_read2_b32 v[72:73], v9 offset0:140 offset1:173
	ds_read2_b32 v[74:75], v9 offset0:206 offset1:239
	ds_read2_b32 v[76:77], v9 offset0:16 offset1:49
	ds_read2_b32 v[78:79], v9 offset0:82 offset1:115
	ds_read2_b32 v[80:81], v9 offset0:148 offset1:181
	ds_read2_b32 v[82:83], v9 offset0:214 offset1:247
	ds_read2_b32 v[84:85], v9 offset0:24 offset1:57
	ds_read2_b32 v[86:87], v9 offset0:90 offset1:123
	ds_read2_b32 v[88:89], v9 offset0:156 offset1:189
	ds_read2_b32 v[90:91], v9 offset0:222 offset1:255
	s_waitcnt lgkmcnt(12)
	v_cvt_pk_bf16_f32 v92, v60, v61
	v_cvt_pk_bf16_f32 v93, v62, v63
	v_cvt_pk_bf16_f32 v94, v64, v65
	v_cvt_pk_bf16_f32 v95, v66, v67
	global_store_dwordx4 v12, v[92:95], s[64:65]
	s_waitcnt lgkmcnt(8)
	v_cvt_pk_bf16_f32 v96, v68, v69
	v_cvt_pk_bf16_f32 v97, v70, v71
	v_cvt_pk_bf16_f32 v98, v72, v73
	v_cvt_pk_bf16_f32 v99, v74, v75
	global_store_dwordx4 v13, v[96:99], s[64:65]
	s_waitcnt lgkmcnt(4)
	v_cvt_pk_bf16_f32 v100, v76, v77
	v_cvt_pk_bf16_f32 v101, v78, v79
	v_cvt_pk_bf16_f32 v102, v80, v81
	v_cvt_pk_bf16_f32 v103, v82, v83
	global_store_dwordx4 v14, v[100:103], s[64:65]
	s_waitcnt lgkmcnt(0)
	v_cvt_pk_bf16_f32 v104, v84, v85
	v_cvt_pk_bf16_f32 v105, v86, v87
	v_cvt_pk_bf16_f32 v106, v88, v89
	v_cvt_pk_bf16_f32 v107, v90, v91
	global_store_dwordx4 v15, v[104:107], s[64:65]
	s_cmpk_lt_i32 s32, 0x1600
	s_cbranch_scc0 .Lxpfd_fin
	s_add_i32 s59, s32, 0x400
	s_cmpk_lt_i32 s59, 0x1600
	s_cbranch_scc0 .Lxpfd_dumA
; #define LAS __attribute__((address_space(3)))
; __device__ __forceinline__ unsigned cvt_pk_bf16(float lo, float hi) { unsigned r; asm volatile("v_cvt_pk_bf16_f32 %0, %1, %2" : "=v"(r) : "v"(lo), "v"(hi)); return r; }
; __device__ __forceinline__ void xpose_item(const float* src, int ld, bf16_t* dst, int K, int k0, LAS float* scr, int lane, const float* gk) {
;     if (src) {
; #pragma unroll 8
;         for (int i = 0; i < 32; ++i) { const int kk = 2 * i + (lane >> 5); scr[kk * 33 + (lane & 31)] = __builtin_nontemporal_load(src + (size_t)(k0 + kk) * ld + (lane & 31)); }
;     } else {
; #pragma unroll 8
;         for (int i = 0; i < 32; ++i) { const int kk = 2 * i + (lane >> 5); scr[kk * 33 + (lane & 31)] = 0.f; }
;     }
;     const int c = lane & 7;
;     f32x4 g0 = (f32x4){1.f, 1.f, 1.f, 1.f}, g1 = g0;
;     if (gk) { g0 = *(const f32x4*)(gk + k0 + 8 * c); g1 = *(const f32x4*)(gk + k0 + 8 * c + 4); }
;     asm volatile("s_waitcnt lgkmcnt(0)" ::: "memory");
; #pragma unroll
;     for (int j = 0; j < 4; ++j) { const int n = (lane >> 3) + 8 * j; const LAS float* s = scr + (8 * c) * 33 + n;
;         u32x4 o; o.x = cvt_pk_bf16(s[0 * 33] * g0[0], s[1 * 33] * g0[1]); o.y = cvt_pk_bf16(s[2 * 33] * g0[2], s[3 * 33] * g0[3]); o.z = cvt_pk_bf16(s[4 * 33] * g1[0], s[5 * 33] * g1[1]); o.w = cvt_pk_bf16(s[6 * 33] * g1[2], s[7 * 33] * g1[3]);
;         *(u32x4*)(dst + (size_t)n * K + k0 + 8 * c) = o; }
;     asm volatile("s_waitcnt lgkmcnt(0)" ::: "memory");
; }
; __global__ void __launch_bounds__(512) mega(Args a_byval) {
;     ...
;             it = xpose_all(a.in[25] + (size_t)lyr * D * DFF, nullptr, 2048, DFF, 2048, 2048, 0, (bf16_t*)(ws + (lyr ? WS_W_D : WS_W_D0)), it, NGW, scr, lane);
	s_lshr_b32 s64, s59, 6
	s_and_b32 s65, s59, 63
	s_lshl_b32 s66, s64, 19
	s_lshl_b32 s67, s65, 7
	s_add_i32 s66, s66, s67
	s_add_u32 s66, s60, s66
	s_addc_u32 s67, s61, 0
	v_mov_b32_e32 v11, v5
	global_load_dword v20, v11, s[66:67] nt
	v_add_u32_e32 v11, 0x4000, v11
	global_load_dword v21, v11, s[66:67] nt
	v_add_u32_e32 v11, 0x4000, v11
	global_load_dword v22, v11, s[66:67] nt
	v_add_u32_e32 v11, 0x4000, v11
	global_load_dword v23, v11, s[66:67] nt
	v_add_u32_e32 v11, 0x4000, v11
	global_load_dword v24, v11, s[66:67] nt
	v_add_u32_e32 v11, 0x4000, v11
	global_load_dword v25, v11, s[66:67] nt
	v_add_u32_e32 v11, 0x4000, v11
	global_load_dword v26, v11, s[66:67] nt
	v_add_u32_e32 v11, 0x4000, v11
	global_load_dword v27, v11, s[66:67] nt
	v_add_u32_e32 v11, 0x4000, v11
	global_load_dword v28, v11, s[66:67] nt
	v_add_u32_e32 v11, 0x4000, v11
	global_load_dword v29, v11, s[66:67] nt
	v_add_u32_e32 v11, 0x4000, v11
	global_load_dword v30, v11, s[66:67] nt
	v_add_u32_e32 v11, 0x4000, v11
	global_load_dword v31, v11, s[66:67] nt
	v_add_u32_e32 v11, 0x4000, v11
	global_load_dword v32, v11, s[66:67] nt
	v_add_u32_e32 v11, 0x4000, v11
	global_load_dword v33, v11, s[66:67] nt
	v_add_u32_e32 v11, 0x4000, v11
	global_load_dword v34, v11, s[66:67] nt
	v_add_u32_e32 v11, 0x4000, v11
	global_load_dword v35, v11, s[66:67] nt
	v_add_u32_e32 v11, 0x4000, v11
	global_load_dword v36, v11, s[66:67] nt
	v_add_u32_e32 v11, 0x4000, v11
	global_load_dword v37, v11, s[66:67] nt
	v_add_u32_e32 v11, 0x4000, v11
	global_load_dword v38, v11, s[66:67] nt
	v_add_u32_e32 v11, 0x4000, v11
	global_load_dword v39, v11, s[66:67] nt
	v_add_u32_e32 v11, 0x4000, v11
	global_load_dword v40, v11, s[66:67] nt
	v_add_u32_e32 v11, 0x4000, v11
	global_load_dword v41, v11, s[66:67] nt
	v_add_u32_e32 v11, 0x4000, v11
	global_load_dword v42, v11, s[66:67] nt
	v_add_u32_e32 v11, 0x4000, v11
	global_load_dword v43, v11, s[66:67] nt
	v_add_u32_e32 v11, 0x4000, v11
	global_load_dword v44, v11, s[66:67] nt
	v_add_u32_e32 v11, 0x4000, v11
	global_load_dword v45, v11, s[66:67] nt
	v_add_u32_e32 v11, 0x4000, v11
	global_load_dword v46, v11, s[66:67] nt
	v_add_u32_e32 v11, 0x4000, v11
	global_load_dword v47, v11, s[66:67] nt
	v_add_u32_e32 v11, 0x4000, v11
	global_load_dword v48, v11, s[66:67] nt
	v_add_u32_e32 v11, 0x4000, v11
	global_load_dword v49, v11, s[66:67] nt
	v_add_u32_e32 v11, 0x4000, v11
	global_load_dword v50, v11, s[66:67] nt
	v_add_u32_e32 v11, 0x4000, v11
	global_load_dword v51, v11, s[66:67] nt
	s_branch .Lxpfd_procB
.Lxpfd_dumA:
	global_load_dword v20, v0, s[60:61]
	global_load_dword v21, v0, s[60:61]
	global_load_dword v22, v0, s[60:61]
	global_load_dword v23, v0, s[60:61]
	global_load_dword v24, v0, s[60:61]
	global_load_dword v25, v0, s[60:61]
	global_load_dword v26, v0, s[60:61]
	global_load_dword v27, v0, s[60:61]
	global_load_dword v28, v0, s[60:61]
	global_load_dword v29, v0, s[60:61]
	global_load_dword v30, v0, s[60:61]
	global_load_dword v31, v0, s[60:61]
	global_load_dword v32, v0, s[60:61]
	global_load_dword v33, v0, s[60:61]
	global_load_dword v34, v0, s[60:61]
	global_load_dword v35, v0, s[60:61]
	global_load_dword v36, v0, s[60:61]
	global_load_dword v37, v0, s[60:61]
	global_load_dword v38, v0, s[60:61]
	global_load_dword v39, v0, s[60:61]
	global_load_dword v40, v0, s[60:61]
	global_load_dword v41, v0, s[60:61]
	global_load_dword v42, v0, s[60:61]
	global_load_dword v43, v0, s[60:61]
	global_load_dword v44, v0, s[60:61]
	global_load_dword v45, v0, s[60:61]
	global_load_dword v46, v0, s[60:61]
	global_load_dword v47, v0, s[60:61]
	global_load_dword v48, v0, s[60:61]
	global_load_dword v49, v0, s[60:61]
	global_load_dword v50, v0, s[60:61]
	global_load_dword v51, v0, s[60:61]
; #define LAS __attribute__((address_space(3)))
; __device__ __forceinline__ unsigned cvt_pk_bf16(float lo, float hi) { unsigned r; asm volatile("v_cvt_pk_bf16_f32 %0, %1, %2" : "=v"(r) : "v"(lo), "v"(hi)); return r; }
; __device__ __forceinline__ void xpose_item(const float* src, int ld, bf16_t* dst, int K, int k0, LAS float* scr, int lane, const float* gk) {
;     if (src) {
; #pragma unroll 8
;         for (int i = 0; i < 32; ++i) { const int kk = 2 * i + (lane >> 5); scr[kk * 33 + (lane & 31)] = __builtin_nontemporal_load(src + (size_t)(k0 + kk) * ld + (lane & 31)); }
;     } else {
; #pragma unroll 8
;         for (int i = 0; i < 32; ++i) { const int kk = 2 * i + (lane >> 5); scr[kk * 33 + (lane & 31)] = 0.f; }
;     }
;     const int c = lane & 7;
;     f32x4 g0 = (f32x4){1.f, 1.f, 1.f, 1.f}, g1 = g0;
;     if (gk) { g0 = *(const f32x4*)(gk + k0 + 8 * c); g1 = *(const f32x4*)(gk + k0 + 8 * c + 4); }
;     asm volatile("s_waitcnt lgkmcnt(0)" ::: "memory");
; #pragma unroll
;     for (int j = 0; j < 4; ++j) { const int n = (lane >> 3) + 8 * j; const LAS float* s = scr + (8 * c) * 33 + n;
;         u32x4 o; o.x = cvt_pk_bf16(s[0 * 33] * g0[0], s[1 * 33] * g0[1]); o.y = cvt_pk_bf16(s[2 * 33] * g0[2], s[3 * 33] * g0[3]); o.z = cvt_pk_bf16(s[4 * 33] * g1[0], s[5 * 33] * g1[1]); o.w = cvt_pk_bf16(s[6 * 33] * g1[2], s[7 * 33] * g1[3]);
;         *(u32x4*)(dst + (size_t)n * K + k0 + 8 * c) = o; }
;     asm volatile("s_waitcnt lgkmcnt(0)" ::: "memory");
; }
; __global__ void __launch_bounds__(512) mega(Args a_byval) {
;     ...
;             it = xpose_all(a.in[25] + (size_t)lyr * D * DFF, nullptr, 2048, DFF, 2048, 2048, 0, (bf16_t*)(ws + (lyr ? WS_W_D : WS_W_D0)), it, NGW, scr, lane);
.Lxpfd_procB:
	s_lshr_b32 s64, s32, 6
	s_and_b32 s65, s32, 63
	s_mul_i32 s68, s65, 0x58000
	s_lshl_b32 s64, s64, 7
	s_add_i32 s68, s68, s64
	s_add_u32 s64, s62, s68
	s_addc_u32 s65, s63, 0
	s_waitcnt vmcnt(63)
	ds_write_b32 v6, v108 offset:0
	s_waitcnt vmcnt(62)
	ds_write_b32 v6, v109 offset:264
	s_waitcnt vmcnt(61)
	ds_write_b32 v6, v110 offset:528
	s_waitcnt vmcnt(60)
	ds_write_b32 v6, v111 offset:792
	s_waitcnt vmcnt(59)
	ds_write_b32 v6, v112 offset:1056
	s_waitcnt vmcnt(58)
	ds_write_b32 v6, v113 offset:1320
	s_waitcnt vmcnt(57)
	ds_write_b32 v6, v114 offset:1584
	s_waitcnt vmcnt(56)
	ds_write_b32 v6, v115 offset:1848
	s_waitcnt vmcnt(55)
	ds_write_b32 v6, v116 offset:2112
	s_waitcnt vmcnt(54)
	ds_write_b32 v6, v117 offset:2376
	s_waitcnt vmcnt(53)
	ds_write_b32 v6, v118 offset:2640
	s_waitcnt vmcnt(52)
	ds_write_b32 v6, v119 offset:2904
	s_waitcnt vmcnt(51)
	ds_write_b32 v6, v120 offset:3168
	s_waitcnt vmcnt(50)
	ds_write_b32 v6, v121 offset:3432
	s_waitcnt vmcnt(49)
	ds_write_b32 v6, v122 offset:3696
	s_waitcnt vmcnt(48)
	ds_write_b32 v6, v123 offset:3960
	s_waitcnt vmcnt(47)
	ds_write_b32 v6, v124 offset:4224
	s_waitcnt vmcnt(46)
	ds_write_b32 v6, v125 offset:4488
	s_waitcnt vmcnt(45)
	ds_write_b32 v6, v126 offset:4752
	s_waitcnt vmcnt(44)
	ds_write_b32 v6, v127 offset:5016
	s_waitcnt vmcnt(43)
	ds_write_b32 v6, v128 offset:5280
	s_waitcnt vmcnt(42)
	ds_write_b32 v6, v129 offset:5544
	s_waitcnt vmcnt(41)
	ds_write_b32 v6, v130 offset:5808
	s_waitcnt vmcnt(40)
	ds_write_b32 v6, v131 offset:6072
	s_waitcnt vmcnt(39)
	ds_write_b32 v6, v132 offset:6336
	s_waitcnt vmcnt(38)
	ds_write_b32 v6, v133 offset:6600
	s_waitcnt vmcnt(37)
	ds_write_b32 v6, v134 offset:6864
	s_waitcnt vmcnt(36)
	ds_write_b32 v6, v135 offset:7128
	s_waitcnt vmcnt(35)
	ds_write_b32 v6, v136 offset:7392
	s_waitcnt vmcnt(34)
	ds_write_b32 v6, v137 offset:7656
	s_waitcnt vmcnt(33)
	ds_write_b32 v6, v138 offset:7920
	s_waitcnt vmcnt(32)
	ds_write_b32 v6, v139 offset:8184
	s_waitcnt lgkmcnt(0)
	ds_read2_b32 v[60:61], v9 offset0:0 offset1:33
	ds_read2_b32 v[62:63], v9 offset0:66 offset1:99
	ds_read2_b32 v[64:65], v9 offset0:132 offset1:165
	ds_read2_b32 v[66:67], v9 offset0:198 offset1:231
	ds_read2_b32 v[68:69], v9 offset0:8 offset1:41
	ds_read2_b32 v[70:71], v9 offset0:74 offset1:107
	ds_read2_b32 v[72:73], v9 offset0:140 offset1:173
	ds_read2_b32 v[74:75], v9 offset0:206 offset1:239
	ds_read2_b32 v[76:77], v9 offset0:16 offset1:49
	ds_read2_b32 v[78:79], v9 offset0:82 offset1:115
	ds_read2_b32 v[80:81], v9 offset0:148 offset1:181
	ds_read2_b32 v[82:83], v9 offset0:214 offset1:247
	ds_read2_b32 v[84:85], v9 offset0:24 offset1:57
	ds_read2_b32 v[86:87], v9 offset0:90 offset1:123
	ds_read2_b32 v[88:89], v9 offset0:156 offset1:189
	ds_read2_b32 v[90:91], v9 offset0:222 offset1:255
	s_waitcnt lgkmcnt(12)
	v_cvt_pk_bf16_f32 v92, v60, v61
	v_cvt_pk_bf16_f32 v93, v62, v63
	v_cvt_pk_bf16_f32 v94, v64, v65
	v_cvt_pk_bf16_f32 v95, v66, v67
	global_store_dwordx4 v12, v[92:95], s[64:65]
	s_waitcnt lgkmcnt(8)
	v_cvt_pk_bf16_f32 v96, v68, v69
	v_cvt_pk_bf16_f32 v97, v70, v71
	v_cvt_pk_bf16_f32 v98, v72, v73
	v_cvt_pk_bf16_f32 v99, v74, v75
	global_store_dwordx4 v13, v[96:99], s[64:65]
	s_waitcnt lgkmcnt(4)
	v_cvt_pk_bf16_f32 v100, v76, v77
	v_cvt_pk_bf16_f32 v101, v78, v79
	v_cvt_pk_bf16_f32 v102, v80, v81
	v_cvt_pk_bf16_f32 v103, v82, v83
	global_store_dwordx4 v14, v[100:103], s[64:65]
	s_waitcnt lgkmcnt(0)
	v_cvt_pk_bf16_f32 v104, v84, v85
	v_cvt_pk_bf16_f32 v105, v86, v87
	v_cvt_pk_bf16_f32 v106, v88, v89
	v_cvt_pk_bf16_f32 v107, v90, v91
	global_store_dwordx4 v15, v[104:107], s[64:65]
	s_cmpk_lt_i32 s59, 0x1600
	s_cbranch_scc1 .Lxpfd_loop
	s_branch .Lxpfd_drain
.Lxpfd_fin:
	s_mov_b32 s59, s32

; #define LAS __attribute__((address_space(3)))
; __device__ __forceinline__ unsigned cvt_pk_bf16(float lo, float hi) { unsigned r; asm volatile("v_cvt_pk_bf16_f32 %0, %1, %2" : "=v"(r) : "v"(lo), "v"(hi)); return r; }
; __device__ __forceinline__ void xpose_item(const float* src, int ld, bf16_t* dst, int K, int k0, LAS float* scr, int lane, const float* gk) {
;     if (src) {
; #pragma unroll 8
;         for (int i = 0; i < 32; ++i) { const int kk = 2 * i + (lane >> 5); scr[kk * 33 + (lane & 31)] = __builtin_nontemporal_load(src + (size_t)(k0 + kk) * ld + (lane & 31)); }
;     } else {
; #pragma unroll 8
;         for (int i = 0; i < 32; ++i) { const int kk = 2 * i + (lane >> 5); scr[kk * 33 + (lane & 31)] = 0.f; }
;     }
;     const int c = lane & 7;
;     f32x4 g0 = (f32x4){1.f, 1.f, 1.f, 1.f}, g1 = g0;
;     if (gk) { g0 = *(const f32x4*)(gk + k0 + 8 * c); g1 = *(const f32x4*)(gk + k0 + 8 * c + 4); }
;     asm volatile("s_waitcnt lgkmcnt(0)" ::: "memory");
; #pragma unroll
;     for (int j = 0; j < 4; ++j) { const int n = (lane >> 3) + 8 * j; const LAS float* s = scr + (8 * c) * 33 + n;
;         u32x4 o; o.x = cvt_pk_bf16(s[0 * 33] * g0[0], s[1 * 33] * g0[1]); o.y = cvt_pk_bf16(s[2 * 33] * g0[2], s[3 * 33] * g0[3]); o.z = cvt_pk_bf16(s[4 * 33] * g1[0], s[5 * 33] * g1[1]); o.w = cvt_pk_bf16(s[6 * 33] * g1[2], s[7 * 33] * g1[3]);
;         *(u32x4*)(dst + (size_t)n * K + k0 + 8 * c) = o; }
;     asm volatile("s_waitcnt lgkmcnt(0)" ::: "memory");
; }
; __global__ void __launch_bounds__(512) mega(Args a_byval) {
;     ...
;                 it = xpose_all(a.in[22], nullptr, 2048, 4096, 2048, 2048, 0, (bf16_t*)(ws + WS_WB_OUT), it, NGW, scr, lane);
.Lxpfd_end:
	s_sub_i32 s59, s59, 0x1600
	s_cmpk_ge_i32 s59, 0x1000
	s_cbranch_scc1 .Lxpwo_end
	s_load_dwordx2 s[60:61], s[92:93], 0xb0
	s_load_dwordx2 s[62:63], s[92:93], 0xe8
	v_mov_b32_e32 v10, 0x2000
	v_mul_u32_u24_e32 v10, v8, v10
	v_lshl_add_u32 v12, v7, 4, v10
	v_add_u32_e32 v13, 0x10000, v12
	v_add_u32_e32 v14, 0x20000, v12
	v_add_u32_e32 v15, 0x30000, v12
	s_waitcnt lgkmcnt(0)
	s_add_u32 s62, s62, 0xad00000
	s_addc_u32 s63, s63, 0
	s_lshr_b32 s64, s59, 6
	s_and_b32 s65, s59, 63
	s_lshl_b32 s66, s64, 19
	s_lshl_b32 s67, s65, 7
	s_add_i32 s66, s66, s67
	s_add_u32 s66, s60, s66
	s_addc_u32 s67, s61, 0
	v_mov_b32_e32 v11, v5
	global_load_dword v20, v11, s[66:67] nt
	v_add_u32_e32 v11, 0x4000, v11
	global_load_dword v21, v11, s[66:67] nt
	v_add_u32_e32 v11, 0x4000, v11
	global_load_dword v22, v11, s[66:67] nt
	v_add_u32_e32 v11, 0x4000, v11
	global_load_dword v23, v11, s[66:67] nt
	v_add_u32_e32 v11, 0x4000, v11
	global_load_dword v24, v11, s[66:67] nt
	v_add_u32_e32 v11, 0x4000, v11
	global_load_dword v25, v11, s[66:67] nt
	v_add_u32_e32 v11, 0x4000, v11
	global_load_dword v26, v11, s[66:67] nt
	v_add_u32_e32 v11, 0x4000, v11
	global_load_dword v27, v11, s[66:67] nt
	v_add_u32_e32 v11, 0x4000, v11
	global_load_dword v28, v11, s[66:67] nt
	v_add_u32_e32 v11, 0x4000, v11
	global_load_dword v29, v11, s[66:67] nt
	v_add_u32_e32 v11, 0x4000, v11
	global_load_dword v30, v11, s[66:67] nt
	v_add_u32_e32 v11, 0x4000, v11
	global_load_dword v31, v11, s[66:67] nt
	v_add_u32_e32 v11, 0x4000, v11
	global_load_dword v32, v11, s[66:67] nt
	v_add_u32_e32 v11, 0x4000, v11
	global_load_dword v33, v11, s[66:67] nt
	v_add_u32_e32 v11, 0x4000, v11
	global_load_dword v34, v11, s[66:67] nt
	v_add_u32_e32 v11, 0x4000, v11
	global_load_dword v35, v11, s[66:67] nt
	v_add_u32_e32 v11, 0x4000, v11
	global_load_dword v36, v11, s[66:67] nt
	v_add_u32_e32 v11, 0x4000, v11
	global_load_dword v37, v11, s[66:67] nt
	v_add_u32_e32 v11, 0x4000, v11
	global_load_dword v38, v11, s[66:67] nt
	v_add_u32_e32 v11, 0x4000, v11
	global_load_dword v39, v11, s[66:67] nt
	v_add_u32_e32 v11, 0x4000, v11
	global_load_dword v40, v11, s[66:67] nt
	v_add_u32_e32 v11, 0x4000, v11
	global_load_dword v41, v11, s[66:67] nt
	v_add_u32_e32 v11, 0x4000, v11
	global_load_dword v42, v11, s[66:67] nt
	v_add_u32_e32 v11, 0x4000, v11
	global_load_dword v43, v11, s[66:67] nt
	v_add_u32_e32 v11, 0x4000, v11
	global_load_dword v44, v11, s[66:67] nt
	v_add_u32_e32 v11, 0x4000, v11
	global_load_dword v45, v11, s[66:67] nt
	v_add_u32_e32 v11, 0x4000, v11
	global_load_dword v46, v11, s[66:67] nt
	v_add_u32_e32 v11, 0x4000, v11
	global_load_dword v47, v11, s[66:67] nt
	v_add_u32_e32 v11, 0x4000, v11
	global_load_dword v48, v11, s[66:67] nt
	v_add_u32_e32 v11, 0x4000, v11
	global_load_dword v49, v11, s[66:67] nt
	v_add_u32_e32 v11, 0x4000, v11
	global_load_dword v50, v11, s[66:67] nt
	v_add_u32_e32 v11, 0x4000, v11
	global_load_dword v51, v11, s[66:67] nt
.Lxpwo_loop:
	s_add_i32 s32, s59, 0x400
	s_cmpk_lt_i32 s32, 0x1000
	s_cbranch_scc0 .Lxpwo_dumB
	s_lshr_b32 s64, s32, 6
	s_and_b32 s65, s32, 63
	s_lshl_b32 s66, s64, 19
	s_lshl_b32 s67, s65, 7
	s_add_i32 s66, s66, s67
	s_add_u32 s66, s60, s66
	s_addc_u32 s67, s61, 0
	v_mov_b32_e32 v11, v5
	global_load_dword v108, v11, s[66:67] nt
	v_add_u32_e32 v11, 0x4000, v11
	global_load_dword v109, v11, s[66:67] nt
	v_add_u32_e32 v11, 0x4000, v11
	global_load_dword v110, v11, s[66:67] nt
	v_add_u32_e32 v11, 0x4000, v11
	global_load_dword v111, v11, s[66:67] nt
	v_add_u32_e32 v11, 0x4000, v11
	global_load_dword v112, v11, s[66:67] nt
	v_add_u32_e32 v11, 0x4000, v11
	global_load_dword v113, v11, s[66:67] nt
	v_add_u32_e32 v11, 0x4000, v11
	global_load_dword v114, v11, s[66:67] nt
	v_add_u32_e32 v11, 0x4000, v11
	global_load_dword v115, v11, s[66:67] nt
	v_add_u32_e32 v11, 0x4000, v11
	global_load_dword v116, v11, s[66:67] nt
	v_add_u32_e32 v11, 0x4000, v11
	global_load_dword v117, v11, s[66:67] nt
	v_add_u32_e32 v11, 0x4000, v11
	global_load_dword v118, v11, s[66:67] nt
	v_add_u32_e32 v11, 0x4000, v11
	global_load_dword v119, v11, s[66:67] nt
	v_add_u32_e32 v11, 0x4000, v11
	global_load_dword v120, v11, s[66:67] nt
	v_add_u32_e32 v11, 0x4000, v11
	global_load_dword v121, v11, s[66:67] nt
	v_add_u32_e32 v11, 0x4000, v11
	global_load_dword v122, v11, s[66:67] nt
	v_add_u32_e32 v11, 0x4000, v11
	global_load_dword v123, v11, s[66:67] nt
	v_add_u32_e32 v11, 0x4000, v11
	global_load_dword v124, v11, s[66:67] nt
	v_add_u32_e32 v11, 0x4000, v11
	global_load_dword v125, v11, s[66:67] nt
	v_add_u32_e32 v11, 0x4000, v11
	global_load_dword v126, v11, s[66:67] nt
	v_add_u32_e32 v11, 0x4000, v11
	global_load_dword v127, v11, s[66:67] nt
	v_add_u32_e32 v11, 0x4000, v11
	global_load_dword v128, v11, s[66:67] nt
	v_add_u32_e32 v11, 0x4000, v11
	global_load_dword v129, v11, s[66:67] nt
	v_add_u32_e32 v11, 0x4000, v11
	global_load_dword v130, v11, s[66:67] nt
	v_add_u32_e32 v11, 0x4000, v11
	global_load_dword v131, v11, s[66:67] nt
	v_add_u32_e32 v11, 0x4000, v11
	global_load_dword v132, v11, s[66:67] nt
	v_add_u32_e32 v11, 0x4000, v11
	global_load_dword v133, v11, s[66:67] nt
	v_add_u32_e32 v11, 0x4000, v11
	global_load_dword v134, v11, s[66:67] nt
	v_add_u32_e32 v11, 0x4000, v11
	global_load_dword v135, v11, s[66:67] nt
	v_add_u32_e32 v11, 0x4000, v11
	global_load_dword v136, v11, s[66:67] nt
	v_add_u32_e32 v11, 0x4000, v11
	global_load_dword v137, v11, s[66:67] nt
	v_add_u32_e32 v11, 0x4000, v11
	global_load_dword v138, v11, s[66:67] nt
	v_add_u32_e32 v11, 0x4000, v11
	global_load_dword v139, v11, s[66:67] nt
	s_branch .Lxpwo_procA

; #define LAS __attribute__((address_space(3)))
; __device__ __forceinline__ unsigned cvt_pk_bf16(float lo, float hi) { unsigned r; asm volatile("v_cvt_pk_bf16_f32 %0, %1, %2" : "=v"(r) : "v"(lo), "v"(hi)); return r; }
; __device__ __forceinline__ void xpose_item(const float* src, int ld, bf16_t* dst, int K, int k0, LAS float* scr, int lane, const float* gk) {
;     if (src) {
; #pragma unroll 8
;         for (int i = 0; i < 32; ++i) { const int kk = 2 * i + (lane >> 5); scr[kk * 33 + (lane & 31)] = __builtin_nontemporal_load(src + (size_t)(k0 + kk) * ld + (lane & 31)); }
;     } else {
; #pragma unroll 8
;         for (int i = 0; i < 32; ++i) { const int kk = 2 * i + (lane >> 5); scr[kk * 33 + (lane & 31)] = 0.f; }
;     }
;     const int c = lane & 7;
;     f32x4 g0 = (f32x4){1.f, 1.f, 1.f, 1.f}, g1 = g0;
;     if (gk) { g0 = *(const f32x4*)(gk + k0 + 8 * c); g1 = *(const f32x4*)(gk + k0 + 8 * c + 4); }
;     asm volatile("s_waitcnt lgkmcnt(0)" ::: "memory");
; #pragma unroll
;     for (int j = 0; j < 4; ++j) { const int n = (lane >> 3) + 8 * j; const LAS float* s = scr + (8 * c) * 33 + n;
;         u32x4 o; o.x = cvt_pk_bf16(s[0 * 33] * g0[0], s[1 * 33] * g0[1]); o.y = cvt_pk_bf16(s[2 * 33] * g0[2], s[3 * 33] * g0[3]); o.z = cvt_pk_bf16(s[4 * 33] * g1[0], s[5 * 33] * g1[1]); o.w = cvt_pk_bf16(s[6 * 33] * g1[2], s[7 * 33] * g1[3]);
;         *(u32x4*)(dst + (size_t)n * K + k0 + 8 * c) = o; }
;     asm volatile("s_waitcnt lgkmcnt(0)" ::: "memory");
; }
; __global__ void __launch_bounds__(512) mega(Args a_byval) {
;     ...
;                 it = xpose_all(a.in[22], nullptr, 2048, 4096, 2048, 2048, 0, (bf16_t*)(ws + WS_WB_OUT), it, NGW, scr, lane);
.Lxpwo_procA:
	s_lshr_b32 s64, s59, 6
	s_and_b32 s65, s59, 63
	s_mul_i32 s68, s65, 0x40000
	s_lshl_b32 s64, s64, 7
	s_add_i32 s68, s68, s64
	s_add_u32 s64, s62, s68
	s_addc_u32 s65, s63, 0
	s_waitcnt vmcnt(63)
	ds_write_b32 v6, v20 offset:0
	s_waitcnt vmcnt(62)
	ds_write_b32 v6, v21 offset:264
	s_waitcnt vmcnt(61)
	ds_write_b32 v6, v22 offset:528
	s_waitcnt vmcnt(60)
	ds_write_b32 v6, v23 offset:792
	s_waitcnt vmcnt(59)
	ds_write_b32 v6, v24 offset:1056
	s_waitcnt vmcnt(58)
	ds_write_b32 v6, v25 offset:1320
	s_waitcnt vmcnt(57)
	ds_write_b32 v6, v26 offset:1584
	s_waitcnt vmcnt(56)
	ds_write_b32 v6, v27 offset:1848
	s_waitcnt vmcnt(55)
	ds_write_b32 v6, v28 offset:2112
	s_waitcnt vmcnt(54)
	ds_write_b32 v6, v29 offset:2376
	s_waitcnt vmcnt(53)
	ds_write_b32 v6, v30 offset:2640
	s_waitcnt vmcnt(52)
	ds_write_b32 v6, v31 offset:2904
	s_waitcnt vmcnt(51)
	ds_write_b32 v6, v32 offset:3168
	s_waitcnt vmcnt(50)
	ds_write_b32 v6, v33 offset:3432
	s_waitcnt vmcnt(49)
	ds_write_b32 v6, v34 offset:3696
	s_waitcnt vmcnt(48)
	ds_write_b32 v6, v35 offset:3960
	s_waitcnt vmcnt(47)
	ds_write_b32 v6, v36 offset:4224
	s_waitcnt vmcnt(46)
	ds_write_b32 v6, v37 offset:4488
	s_waitcnt vmcnt(45)
	ds_write_b32 v6, v38 offset:4752
	s_waitcnt vmcnt(44)
	ds_write_b32 v6, v39 offset:5016
	s_waitcnt vmcnt(43)
	ds_write_b32 v6, v40 offset:5280
	s_waitcnt vmcnt(42)
	ds_write_b32 v6, v41 offset:5544
	s_waitcnt vmcnt(41)
	ds_write_b32 v6, v42 offset:5808
	s_waitcnt vmcnt(40)
	ds_write_b32 v6, v43 offset:6072
	s_waitcnt vmcnt(39)
	ds_write_b32 v6, v44 offset:6336
	s_waitcnt vmcnt(38)
	ds_write_b32 v6, v45 offset:6600
	s_waitcnt vmcnt(37)
	ds_write_b32 v6, v46 offset:6864
	s_waitcnt vmcnt(36)
	ds_write_b32 v6, v47 offset:7128
	s_waitcnt vmcnt(35)
	ds_write_b32 v6, v48 offset:7392
	s_waitcnt vmcnt(34)
	ds_write_b32 v6, v49 offset:7656
	s_waitcnt vmcnt(33)
	ds_write_b32 v6, v50 offset:7920
	s_waitcnt vmcnt(32)
	ds_write_b32 v6, v51 offset:8184
	s_waitcnt lgkmcnt(0)
	ds_read2_b32 v[60:61], v9 offset0:0 offset1:33
	ds_read2_b32 v[62:63], v9 offset0:66 offset1:99
	ds_read2_b32 v[64:65], v9 offset0:132 offset1:165
	ds_read2_b32 v[66:67], v9 offset0:198 offset1:231
	ds_read2_b32 v[68:69], v9 offset0:8 offset1:41
	ds_read2_b32 v[70:71], v9 offset0:74 offset1:107
	ds_read2_b32 v[72:73], v9 offset0:140 offset1:173
	ds_read2_b32 v[74:75], v9 offset0:206 offset1:239
	ds_read2_b32 v[76:77], v9 offset0:16 offset1:49
	ds_read2_b32 v[78:79], v9 offset0:82 offset1:115
	ds_read2_b32 v[80:81], v9 offset0:148 offset1:181
	ds_read2_b32 v[82:83], v9 offset0:214 offset1:247
	ds_read2_b32 v[84:85], v9 offset0:24 offset1:57
	ds_read2_b32 v[86:87], v9 offset0:90 offset1:123
	ds_read2_b32 v[88:89], v9 offset0:156 offset1:189
	ds_read2_b32 v[90:91], v9 offset0:222 offset1:255
	s_waitcnt lgkmcnt(12)
	v_cvt_pk_bf16_f32 v92, v60, v61
	v_cvt_pk_bf16_f32 v93, v62, v63
	v_cvt_pk_bf16_f32 v94, v64, v65
	v_cvt_pk_bf16_f32 v95, v66, v67
	global_store_dwordx4 v12, v[92:95], s[64:65]
	s_waitcnt lgkmcnt(8)
	v_cvt_pk_bf16_f32 v96, v68, v69
	v_cvt_pk_bf16_f32 v97, v70, v71
	v_cvt_pk_bf16_f32 v98, v72, v73
	v_cvt_pk_bf16_f32 v99, v74, v75
	global_store_dwordx4 v13, v[96:99], s[64:65]
	s_waitcnt lgkmcnt(4)
	v_cvt_pk_bf16_f32 v100, v76, v77
	v_cvt_pk_bf16_f32 v101, v78, v79
	v_cvt_pk_bf16_f32 v102, v80, v81
	v_cvt_pk_bf16_f32 v103, v82, v83
	global_store_dwordx4 v14, v[100:103], s[64:65]
	s_waitcnt lgkmcnt(0)
	v_cvt_pk_bf16_f32 v104, v84, v85
	v_cvt_pk_bf16_f32 v105, v86, v87
	v_cvt_pk_bf16_f32 v106, v88, v89
	v_cvt_pk_bf16_f32 v107, v90, v91
	global_store_dwordx4 v15, v[104:107], s[64:65]
	s_cmpk_lt_i32 s32, 0x1000
	s_cbranch_scc0 .Lxpwo_fin
	s_add_i32 s59, s32, 0x400
	s_cmpk_lt_i32 s59, 0x1000
	s_cbranch_scc0 .Lxpwo_dumA
	s_lshr_b32 s64, s59, 6
	s_and_b32 s65, s59, 63
	s_lshl_b32 s66, s64, 19
	s_lshl_b32 s67, s65, 7
	s_add_i32 s66, s66, s67
	s_add_u32 s66, s60, s66
	s_addc_u32 s67, s61, 0
	v_mov_b32_e32 v11, v5
	global_load_dword v20, v11, s[66:67] nt
	v_add_u32_e32 v11, 0x4000, v11
	global_load_dword v21, v11, s[66:67] nt
	v_add_u32_e32 v11, 0x4000, v11
	global_load_dword v22, v11, s[66:67] nt
	v_add_u32_e32 v11, 0x4000, v11
	global_load_dword v23, v11, s[66:67] nt
	v_add_u32_e32 v11, 0x4000, v11
	global_load_dword v24, v11, s[66:67] nt
	v_add_u32_e32 v11, 0x4000, v11
	global_load_dword v25, v11, s[66:67] nt
	v_add_u32_e32 v11, 0x4000, v11
	global_load_dword v26, v11, s[66:67] nt
	v_add_u32_e32 v11, 0x4000, v11
	global_load_dword v27, v11, s[66:67] nt
	v_add_u32_e32 v11, 0x4000, v11
	global_load_dword v28, v11, s[66:67] nt
	v_add_u32_e32 v11, 0x4000, v11
	global_load_dword v29, v11, s[66:67] nt
	v_add_u32_e32 v11, 0x4000, v11
	global_load_dword v30, v11, s[66:67] nt
	v_add_u32_e32 v11, 0x4000, v11
	global_load_dword v31, v11, s[66:67] nt
	v_add_u32_e32 v11, 0x4000, v11
	global_load_dword v32, v11, s[66:67] nt
	v_add_u32_e32 v11, 0x4000, v11
	global_load_dword v33, v11, s[66:67] nt
	v_add_u32_e32 v11, 0x4000, v11
	global_load_dword v34, v11, s[66:67] nt
	v_add_u32_e32 v11, 0x4000, v11
	global_load_dword v35, v11, s[66:67] nt
	v_add_u32_e32 v11, 0x4000, v11
	global_load_dword v36, v11, s[66:67] nt
	v_add_u32_e32 v11, 0x4000, v11
	global_load_dword v37, v11, s[66:67] nt
	v_add_u32_e32 v11, 0x4000, v11
	global_load_dword v38, v11, s[66:67] nt
	v_add_u32_e32 v11, 0x4000, v11
	global_load_dword v39, v11, s[66:67] nt
	v_add_u32_e32 v11, 0x4000, v11
	global_load_dword v40, v11, s[66:67] nt
	v_add_u32_e32 v11, 0x4000, v11
	global_load_dword v41, v11, s[66:67] nt
	v_add_u32_e32 v11, 0x4000, v11
	global_load_dword v42, v11, s[66:67] nt
	v_add_u32_e32 v11, 0x4000, v11
	global_load_dword v43, v11, s[66:67] nt
	v_add_u32_e32 v11, 0x4000, v11
	global_load_dword v44, v11, s[66:67] nt
	v_add_u32_e32 v11, 0x4000, v11
	global_load_dword v45, v11, s[66:67] nt
	v_add_u32_e32 v11, 0x4000, v11
	global_load_dword v46, v11, s[66:67] nt
	v_add_u32_e32 v11, 0x4000, v11
	global_load_dword v47, v11, s[66:67] nt
	v_add_u32_e32 v11, 0x4000, v11
	global_load_dword v48, v11, s[66:67] nt
	v_add_u32_e32 v11, 0x4000, v11
	global_load_dword v49, v11, s[66:67] nt
	v_add_u32_e32 v11, 0x4000, v11
	global_load_dword v50, v11, s[66:67] nt
	v_add_u32_e32 v11, 0x4000, v11
	global_load_dword v51, v11, s[66:67] nt
	s_branch .Lxpwo_procB

; #define LAS __attribute__((address_space(3)))
; __device__ __forceinline__ unsigned cvt_pk_bf16(float lo, float hi) { unsigned r; asm volatile("v_cvt_pk_bf16_f32 %0, %1, %2" : "=v"(r) : "v"(lo), "v"(hi)); return r; }
; __device__ __forceinline__ void xpose_item(const float* src, int ld, bf16_t* dst, int K, int k0, LAS float* scr, int lane, const float* gk) {
;     if (src) {
; #pragma unroll 8
;         for (int i = 0; i < 32; ++i) { const int kk = 2 * i + (lane >> 5); scr[kk * 33 + (lane & 31)] = __builtin_nontemporal_load(src + (size_t)(k0 + kk) * ld + (lane & 31)); }
;     } else {
; #pragma unroll 8
;         for (int i = 0; i < 32; ++i) { const int kk = 2 * i + (lane >> 5); scr[kk * 33 + (lane & 31)] = 0.f; }
;     }
;     const int c = lane & 7;
;     f32x4 g0 = (f32x4){1.f, 1.f, 1.f, 1.f}, g1 = g0;
;     if (gk) { g0 = *(const f32x4*)(gk + k0 + 8 * c); g1 = *(const f32x4*)(gk + k0 + 8 * c + 4); }
;     asm volatile("s_waitcnt lgkmcnt(0)" ::: "memory");
; #pragma unroll
;     for (int j = 0; j < 4; ++j) { const int n = (lane >> 3) + 8 * j; const LAS float* s = scr + (8 * c) * 33 + n;
;         u32x4 o; o.x = cvt_pk_bf16(s[0 * 33] * g0[0], s[1 * 33] * g0[1]); o.y = cvt_pk_bf16(s[2 * 33] * g0[2], s[3 * 33] * g0[3]); o.z = cvt_pk_bf16(s[4 * 33] * g1[0], s[5 * 33] * g1[1]); o.w = cvt_pk_bf16(s[6 * 33] * g1[2], s[7 * 33] * g1[3]);
;         *(u32x4*)(dst + (size_t)n * K + k0 + 8 * c) = o; }
;     asm volatile("s_waitcnt lgkmcnt(0)" ::: "memory");
; }
; __global__ void __launch_bounds__(512) mega(Args a_byval) {
;     ...
;                 it = xpose_all(a.in[22], nullptr, 2048, 4096, 2048, 2048, 0, (bf16_t*)(ws + WS_WB_OUT), it, NGW, scr, lane);
.Lxpwo_procB:
	s_lshr_b32 s64, s32, 6
	s_and_b32 s65, s32, 63
	s_mul_i32 s68, s65, 0x40000
	s_lshl_b32 s64, s64, 7
	s_add_i32 s68, s68, s64
	s_add_u32 s64, s62, s68
	s_addc_u32 s65, s63, 0
	s_waitcnt vmcnt(63)
	ds_write_b32 v6, v108 offset:0
	s_waitcnt vmcnt(62)
	ds_write_b32 v6, v109 offset:264
	s_waitcnt vmcnt(61)
	ds_write_b32 v6, v110 offset:528
	s_waitcnt vmcnt(60)
	ds_write_b32 v6, v111 offset:792
	s_waitcnt vmcnt(59)
	ds_write_b32 v6, v112 offset:1056
	s_waitcnt vmcnt(58)
	ds_write_b32 v6, v113 offset:1320
	s_waitcnt vmcnt(57)
	ds_write_b32 v6, v114 offset:1584
	s_waitcnt vmcnt(56)
	ds_write_b32 v6, v115 offset:1848
	s_waitcnt vmcnt(55)
	ds_write_b32 v6, v116 offset:2112
	s_waitcnt vmcnt(54)
	ds_write_b32 v6, v117 offset:2376
	s_waitcnt vmcnt(53)
	ds_write_b32 v6, v118 offset:2640
	s_waitcnt vmcnt(52)
	ds_write_b32 v6, v119 offset:2904
	s_waitcnt vmcnt(51)
	ds_write_b32 v6, v120 offset:3168
	s_waitcnt vmcnt(50)
	ds_write_b32 v6, v121 offset:3432
	s_waitcnt vmcnt(49)
	ds_write_b32 v6, v122 offset:3696
	s_waitcnt vmcnt(48)
	ds_write_b32 v6, v123 offset:3960
	s_waitcnt vmcnt(47)
	ds_write_b32 v6, v124 offset:4224
	s_waitcnt vmcnt(46)
	ds_write_b32 v6, v125 offset:4488
	s_waitcnt vmcnt(45)
	ds_write_b32 v6, v126 offset:4752
	s_waitcnt vmcnt(44)
	ds_write_b32 v6, v127 offset:5016
	s_waitcnt vmcnt(43)
	ds_write_b32 v6, v128 offset:5280
	s_waitcnt vmcnt(42)
	ds_write_b32 v6, v129 offset:5544
	s_waitcnt vmcnt(41)
	ds_write_b32 v6, v130 offset:5808
	s_waitcnt vmcnt(40)
	ds_write_b32 v6, v131 offset:6072
	s_waitcnt vmcnt(39)
	ds_write_b32 v6, v132 offset:6336
	s_waitcnt vmcnt(38)
	ds_write_b32 v6, v133 offset:6600
	s_waitcnt vmcnt(37)
	ds_write_b32 v6, v134 offset:6864
	s_waitcnt vmcnt(36)
	ds_write_b32 v6, v135 offset:7128
	s_waitcnt vmcnt(35)
	ds_write_b32 v6, v136 offset:7392
	s_waitcnt vmcnt(34)
	ds_write_b32 v6, v137 offset:7656
	s_waitcnt vmcnt(33)
	ds_write_b32 v6, v138 offset:7920
	s_waitcnt vmcnt(32)
	ds_write_b32 v6, v139 offset:8184
	s_waitcnt lgkmcnt(0)
	ds_read2_b32 v[60:61], v9 offset0:0 offset1:33
	ds_read2_b32 v[62:63], v9 offset0:66 offset1:99
	ds_read2_b32 v[64:65], v9 offset0:132 offset1:165
	ds_read2_b32 v[66:67], v9 offset0:198 offset1:231
	ds_read2_b32 v[68:69], v9 offset0:8 offset1:41
	ds_read2_b32 v[70:71], v9 offset0:74 offset1:107
	ds_read2_b32 v[72:73], v9 offset0:140 offset1:173
	ds_read2_b32 v[74:75], v9 offset0:206 offset1:239
	ds_read2_b32 v[76:77], v9 offset0:16 offset1:49
	ds_read2_b32 v[78:79], v9 offset0:82 offset1:115
	ds_read2_b32 v[80:81], v9 offset0:148 offset1:181
	ds_read2_b32 v[82:83], v9 offset0:214 offset1:247
	ds_read2_b32 v[84:85], v9 offset0:24 offset1:57
	ds_read2_b32 v[86:87], v9 offset0:90 offset1:123
	ds_read2_b32 v[88:89], v9 offset0:156 offset1:189
	ds_read2_b32 v[90:91], v9 offset0:222 offset1:255
	s_waitcnt lgkmcnt(12)
	v_cvt_pk_bf16_f32 v92, v60, v61
	v_cvt_pk_bf16_f32 v93, v62, v63
	v_cvt_pk_bf16_f32 v94, v64, v65
	v_cvt_pk_bf16_f32 v95, v66, v67
	global_store_dwordx4 v12, v[92:95], s[64:65]
	s_waitcnt lgkmcnt(8)
	v_cvt_pk_bf16_f32 v96, v68, v69
	v_cvt_pk_bf16_f32 v97, v70, v71
	v_cvt_pk_bf16_f32 v98, v72, v73
	v_cvt_pk_bf16_f32 v99, v74, v75
	global_store_dwordx4 v13, v[96:99], s[64:65]
	s_waitcnt lgkmcnt(4)
	v_cvt_pk_bf16_f32 v100, v76, v77
	v_cvt_pk_bf16_f32 v101, v78, v79
	v_cvt_pk_bf16_f32 v102, v80, v81
	v_cvt_pk_bf16_f32 v103, v82, v83
	global_store_dwordx4 v14, v[100:103], s[64:65]
	s_waitcnt lgkmcnt(0)
	v_cvt_pk_bf16_f32 v104, v84, v85
	v_cvt_pk_bf16_f32 v105, v86, v87
	v_cvt_pk_bf16_f32 v106, v88, v89
	v_cvt_pk_bf16_f32 v107, v90, v91
	global_store_dwordx4 v15, v[104:107], s[64:65]
	s_cmpk_lt_i32 s59, 0x1000
	s_cbranch_scc1 .Lxpwo_loop
	s_branch .Lxpwo_drain

; #define LAS __attribute__((address_space(3)))
; __device__ __forceinline__ unsigned cvt_pk_bf16(float lo, float hi) { unsigned r; asm volatile("v_cvt_pk_bf16_f32 %0, %1, %2" : "=v"(r) : "v"(lo), "v"(hi)); return r; }
; __device__ __forceinline__ void xpose_item(const float* src, int ld, bf16_t* dst, int K, int k0, LAS float* scr, int lane, const float* gk) {
;     if (src) {
; #pragma unroll 8
;         for (int i = 0; i < 32; ++i) { const int kk = 2 * i + (lane >> 5); scr[kk * 33 + (lane & 31)] = __builtin_nontemporal_load(src + (size_t)(k0 + kk) * ld + (lane & 31)); }
;     } else {
; #pragma unroll 8
;         for (int i = 0; i < 32; ++i) { const int kk = 2 * i + (lane >> 5); scr[kk * 33 + (lane & 31)] = 0.f; }
;     }
;     const int c = lane & 7;
;     f32x4 g0 = (f32x4){1.f, 1.f, 1.f, 1.f}, g1 = g0;
;     if (gk) { g0 = *(const f32x4*)(gk + k0 + 8 * c); g1 = *(const f32x4*)(gk + k0 + 8 * c + 4); }
;     asm volatile("s_waitcnt lgkmcnt(0)" ::: "memory");
; #pragma unroll
;     for (int j = 0; j < 4; ++j) { const int n = (lane >> 3) + 8 * j; const LAS float* s = scr + (8 * c) * 33 + n;
;         u32x4 o; o.x = cvt_pk_bf16(s[0 * 33] * g0[0], s[1 * 33] * g0[1]); o.y = cvt_pk_bf16(s[2 * 33] * g0[2], s[3 * 33] * g0[3]); o.z = cvt_pk_bf16(s[4 * 33] * g1[0], s[5 * 33] * g1[1]); o.w = cvt_pk_bf16(s[6 * 33] * g1[2], s[7 * 33] * g1[3]);
;         *(u32x4*)(dst + (size_t)n * K + k0 + 8 * c) = o; }
;     asm volatile("s_waitcnt lgkmcnt(0)" ::: "memory");
; }
; __global__ void __launch_bounds__(512) mega(Args a_byval) {
;     ...
;             it = xpose_all(a.in[27] + (size_t)lyr * D * D, nullptr, 2048, 2048, 2048, 2048, 0, (bf16_t*)(ws + (lyr ? WS_W_PG1 : WS_W_PG)), it, NGW, scr, lane, norm_ple_g + lyr * D);
.Lxpwo_end:
	s_sub_i32 s59, s59, 0x1000
.Lxt7_done:
	s_cmp_lg_u32 s76, 19
	s_cbranch_scc1 .Lxt19_done
	v_readlane_b32 s59, v255, 5
	s_cmpk_lg_i32 s59, 0x100
	s_cbranch_scc1 .Lxt19_done
	s_cmpk_lt_i32 s94, 0x80
	s_cbranch_scc1 .Lxt19_done
	s_sub_i32 s59, s94, 0x80
	s_lshl_b32 s59, s59, 3
	s_add_i32 s59, s59, s95
	s_mul_i32 s64, s95, 0x2100
	v_and_b32_e32 v2, 31, v200
	v_lshrrev_b32_e32 v3, 5, v200
	v_lshlrev_b32_e32 v4, 2, v2
	v_lshl_add_u32 v5, v3, 13, v4
	v_mul_u32_u24_e32 v6, 0x84, v3
	v_add3_u32 v6, v6, v4, s64
	v_and_b32_e32 v7, 7, v200
	v_lshrrev_b32_e32 v8, 3, v200
	v_mul_u32_u24_e32 v9, 0x420, v7
	v_lshl_add_u32 v9, v8, 2, v9
	v_add_u32_e32 v9, s64, v9
	s_cmpk_ge_i32 s59, 0x800
	s_cbranch_scc1 .Lxppg_end
	s_load_dwordx2 s[60:61], s[92:93], 0xd8
	s_load_dwordx2 s[62:63], s[92:93], 0xe8
	s_load_dwordx2 s[64:65], s[92:93], 0x20
	v_mov_b32_e32 v10, 0x1000
	v_mul_u32_u24_e32 v10, v8, v10
	v_lshl_add_u32 v12, v7, 4, v10
	v_add_u32_e32 v13, 0x8000, v12
	v_add_u32_e32 v14, 0x10000, v12
	v_add_u32_e32 v15, 0x18000, v12
	s_waitcnt lgkmcnt(0)
	s_add_u32 s60, s60, 0x1000000
	s_addc_u32 s61, s61, 0
	s_add_u32 s62, s62, 0x1a00000
	s_addc_u32 s63, s63, 0
	s_add_u32 s64, s64, 0x2000
	s_addc_u32 s65, s65, 0
	v_lshlrev_b32_e32 v16, 5, v7
	v_mov_b32_e32 v17, v0
	v_lshl_add_u64 v[16:17], s[64:65], 0, v[16:17]
	s_lshr_b32 s64, s59, 6
	s_and_b32 s65, s59, 63
	s_lshl_b32 s66, s64, 19
	s_lshl_b32 s67, s65, 7
	s_add_i32 s66, s66, s67
	s_add_u32 s66, s60, s66
	s_addc_u32 s67, s61, 0
	s_lshl_b32 s64, s64, 8
	s_mov_b32 s65, 0
	v_lshl_add_u64 v[18:19], s[64:65], 0, v[16:17]
	global_load_dwordx4 v[52:55], v[18:19], off
	global_load_dwordx4 v[56:59], v[18:19], off offset:16
	v_mov_b32_e32 v11, v5
	global_load_dword v20, v11, s[66:67] nt
	v_add_u32_e32 v11, 0x4000, v11
	global_load_dword v21, v11, s[66:67] nt
	v_add_u32_e32 v11, 0x4000, v11
	global_load_dword v22, v11, s[66:67] nt
	v_add_u32_e32 v11, 0x4000, v11
	global_load_dword v23, v11, s[66:67] nt
	v_add_u32_e32 v11, 0x4000, v11
	global_load_dword v24, v11, s[66:67] nt
	v_add_u32_e32 v11, 0x4000, v11
	global_load_dword v25, v11, s[66:67] nt
	v_add_u32_e32 v11, 0x4000, v11
	global_load_dword v26, v11, s[66:67] nt
	v_add_u32_e32 v11, 0x4000, v11
	global_load_dword v27, v11, s[66:67] nt
	v_add_u32_e32 v11, 0x4000, v11
	global_load_dword v28, v11, s[66:67] nt
	v_add_u32_e32 v11, 0x4000, v11
	global_load_dword v29, v11, s[66:67] nt
	v_add_u32_e32 v11, 0x4000, v11
	global_load_dword v30, v11, s[66:67] nt
	v_add_u32_e32 v11, 0x4000, v11
	global_load_dword v31, v11, s[66:67] nt
	v_add_u32_e32 v11, 0x4000, v11
	global_load_dword v32, v11, s[66:67] nt
	v_add_u32_e32 v11, 0x4000, v11
	global_load_dword v33, v11, s[66:67] nt
	v_add_u32_e32 v11, 0x4000, v11
	global_load_dword v34, v11, s[66:67] nt
	v_add_u32_e32 v11, 0x4000, v11
	global_load_dword v35, v11, s[66:67] nt
	v_add_u32_e32 v11, 0x4000, v11
	global_load_dword v36, v11, s[66:67] nt
	v_add_u32_e32 v11, 0x4000, v11
	global_load_dword v37, v11, s[66:67] nt
	v_add_u32_e32 v11, 0x4000, v11
	global_load_dword v38, v11, s[66:67] nt
	v_add_u32_e32 v11, 0x4000, v11
	global_load_dword v39, v11, s[66:67] nt
	v_add_u32_e32 v11, 0x4000, v11
	global_load_dword v40, v11, s[66:67] nt
	v_add_u32_e32 v11, 0x4000, v11
	global_load_dword v41, v11, s[66:67] nt
	v_add_u32_e32 v11, 0x4000, v11
	global_load_dword v42, v11, s[66:67] nt
	v_add_u32_e32 v11, 0x4000, v11
	global_load_dword v43, v11, s[66:67] nt
	v_add_u32_e32 v11, 0x4000, v11
	global_load_dword v44, v11, s[66:67] nt
	v_add_u32_e32 v11, 0x4000, v11
	global_load_dword v45, v11, s[66:67] nt
	v_add_u32_e32 v11, 0x4000, v11
	global_load_dword v46, v11, s[66:67] nt
	v_add_u32_e32 v11, 0x4000, v11
	global_load_dword v47, v11, s[66:67] nt
	v_add_u32_e32 v11, 0x4000, v11
	global_load_dword v48, v11, s[66:67] nt
	v_add_u32_e32 v11, 0x4000, v11
	global_load_dword v49, v11, s[66:67] nt
	v_add_u32_e32 v11, 0x4000, v11
	global_load_dword v50, v11, s[66:67] nt
	v_add_u32_e32 v11, 0x4000, v11
	global_load_dword v51, v11, s[66:67] nt
.Lxppg_loop:
	s_add_i32 s32, s59, 0x400
	s_cmpk_lt_i32 s32, 0x800
	s_cbranch_scc0 .Lxppg_dumB
	s_lshr_b32 s64, s32, 6
	s_and_b32 s65, s32, 63
	s_lshl_b32 s66, s64, 19
	s_lshl_b32 s67, s65, 7
	s_add_i32 s66, s66, s67
	s_add_u32 s66, s60, s66
	s_addc_u32 s67, s61, 0
	s_lshl_b32 s64, s64, 8
	s_mov_b32 s65, 0
	v_lshl_add_u64 v[18:19], s[64:65], 0, v[16:17]
	global_load_dwordx4 v[160:163], v[18:19], off
	global_load_dwordx4 v[164:167], v[18:19], off offset:16
	v_mov_b32_e32 v11, v5
	global_load_dword v108, v11, s[66:67] nt
	v_add_u32_e32 v11, 0x4000, v11
	global_load_dword v109, v11, s[66:67] nt
	v_add_u32_e32 v11, 0x4000, v11
	global_load_dword v110, v11, s[66:67] nt
	v_add_u32_e32 v11, 0x4000, v11
	global_load_dword v111, v11, s[66:67] nt
	v_add_u32_e32 v11, 0x4000, v11
	global_load_dword v112, v11, s[66:67] nt
	v_add_u32_e32 v11, 0x4000, v11
	global_load_dword v113, v11, s[66:67] nt
	v_add_u32_e32 v11, 0x4000, v11
	global_load_dword v114, v11, s[66:67] nt
	v_add_u32_e32 v11, 0x4000, v11
	global_load_dword v115, v11, s[66:67] nt
	v_add_u32_e32 v11, 0x4000, v11
	global_load_dword v116, v11, s[66:67] nt
	v_add_u32_e32 v11, 0x4000, v11
	global_load_dword v117, v11, s[66:67] nt
	v_add_u32_e32 v11, 0x4000, v11
	global_load_dword v118, v11, s[66:67] nt
	v_add_u32_e32 v11, 0x4000, v11
	global_load_dword v119, v11, s[66:67] nt
	v_add_u32_e32 v11, 0x4000, v11
	global_load_dword v120, v11, s[66:67] nt
	v_add_u32_e32 v11, 0x4000, v11
	global_load_dword v121, v11, s[66:67] nt
	v_add_u32_e32 v11, 0x4000, v11
	global_load_dword v122, v11, s[66:67] nt
	v_add_u32_e32 v11, 0x4000, v11
	global_load_dword v123, v11, s[66:67] nt
	v_add_u32_e32 v11, 0x4000, v11
	global_load_dword v124, v11, s[66:67] nt
	v_add_u32_e32 v11, 0x4000, v11
	global_load_dword v125, v11, s[66:67] nt
	v_add_u32_e32 v11, 0x4000, v11
	global_load_dword v126, v11, s[66:67] nt
	v_add_u32_e32 v11, 0x4000, v11
	global_load_dword v127, v11, s[66:67] nt
	v_add_u32_e32 v11, 0x4000, v11
	global_load_dword v128, v11, s[66:67] nt
	v_add_u32_e32 v11, 0x4000, v11
	global_load_dword v129, v11, s[66:67] nt
	v_add_u32_e32 v11, 0x4000, v11
	global_load_dword v130, v11, s[66:67] nt
	v_add_u32_e32 v11, 0x4000, v11
	global_load_dword v131, v11, s[66:67] nt
	v_add_u32_e32 v11, 0x4000, v11
	global_load_dword v132, v11, s[66:67] nt
	v_add_u32_e32 v11, 0x4000, v11
	global_load_dword v133, v11, s[66:67] nt
	v_add_u32_e32 v11, 0x4000, v11
	global_load_dword v134, v11, s[66:67] nt
	v_add_u32_e32 v11, 0x4000, v11
	global_load_dword v135, v11, s[66:67] nt
	v_add_u32_e32 v11, 0x4000, v11
	global_load_dword v136, v11, s[66:67] nt
	v_add_u32_e32 v11, 0x4000, v11
	global_load_dword v137, v11, s[66:67] nt
	v_add_u32_e32 v11, 0x4000, v11
	global_load_dword v138, v11, s[66:67] nt
	v_add_u32_e32 v11, 0x4000, v11
	global_load_dword v139, v11, s[66:67] nt
	s_branch .Lxppg_procA
; #define LAS __attribute__((address_space(3)))
; __device__ __forceinline__ unsigned cvt_pk_bf16(float lo, float hi) { unsigned r; asm volatile("v_cvt_pk_bf16_f32 %0, %1, %2" : "=v"(r) : "v"(lo), "v"(hi)); return r; }
; __device__ __forceinline__ void xpose_item(const float* src, int ld, bf16_t* dst, int K, int k0, LAS float* scr, int lane, const float* gk) {
;     if (src) {
; #pragma unroll 8
;         for (int i = 0; i < 32; ++i) { const int kk = 2 * i + (lane >> 5); scr[kk * 33 + (lane & 31)] = __builtin_nontemporal_load(src + (size_t)(k0 + kk) * ld + (lane & 31)); }
;     } else {
; #pragma unroll 8
;         for (int i = 0; i < 32; ++i) { const int kk = 2 * i + (lane >> 5); scr[kk * 33 + (lane & 31)] = 0.f; }
;     }
;     const int c = lane & 7;
;     f32x4 g0 = (f32x4){1.f, 1.f, 1.f, 1.f}, g1 = g0;
;     if (gk) { g0 = *(const f32x4*)(gk + k0 + 8 * c); g1 = *(const f32x4*)(gk + k0 + 8 * c + 4); }
;     asm volatile("s_waitcnt lgkmcnt(0)" ::: "memory");
; #pragma unroll
;     for (int j = 0; j < 4; ++j) { const int n = (lane >> 3) + 8 * j; const LAS float* s = scr + (8 * c) * 33 + n;
;         u32x4 o; o.x = cvt_pk_bf16(s[0 * 33] * g0[0], s[1 * 33] * g0[1]); o.y = cvt_pk_bf16(s[2 * 33] * g0[2], s[3 * 33] * g0[3]); o.z = cvt_pk_bf16(s[4 * 33] * g1[0], s[5 * 33] * g1[1]); o.w = cvt_pk_bf16(s[6 * 33] * g1[2], s[7 * 33] * g1[3]);
;         *(u32x4*)(dst + (size_t)n * K + k0 + 8 * c) = o; }
;     asm volatile("s_waitcnt lgkmcnt(0)" ::: "memory");
; }
; __global__ void __launch_bounds__(512) mega(Args a_byval) {
;     ...
;             it = xpose_all(a.in[27] + (size_t)lyr * D * D, nullptr, 2048, 2048, 2048, 2048, 0, (bf16_t*)(ws + (lyr ? WS_W_PG1 : WS_W_PG)), it, NGW, scr, lane, norm_ple_g + lyr * D);
.Lxppg_dumB:
	global_load_dwordx4 v[160:163], v[16:17], off
	global_load_dwordx4 v[164:167], v[16:17], off
	global_load_dword v108, v0, s[60:61]
	global_load_dword v109, v0, s[60:61]
	global_load_dword v110, v0, s[60:61]
	global_load_dword v111, v0, s[60:61]
	global_load_dword v112, v0, s[60:61]
	global_load_dword v113, v0, s[60:61]
	global_load_dword v114, v0, s[60:61]
	global_load_dword v115, v0, s[60:61]
	global_load_dword v116, v0, s[60:61]
	global_load_dword v117, v0, s[60:61]
	global_load_dword v118, v0, s[60:61]
	global_load_dword v119, v0, s[60:61]
	global_load_dword v120, v0, s[60:61]
	global_load_dword v121, v0, s[60:61]
	global_load_dword v122, v0, s[60:61]
	global_load_dword v123, v0, s[60:61]
	global_load_dword v124, v0, s[60:61]
	global_load_dword v125, v0, s[60:61]
	global_load_dword v126, v0, s[60:61]
	global_load_dword v127, v0, s[60:61]
	global_load_dword v128, v0, s[60:61]
	global_load_dword v129, v0, s[60:61]
	global_load_dword v130, v0, s[60:61]
	global_load_dword v131, v0, s[60:61]
	global_load_dword v132, v0, s[60:61]
	global_load_dword v133, v0, s[60:61]
	global_load_dword v134, v0, s[60:61]
	global_load_dword v135, v0, s[60:61]
	global_load_dword v136, v0, s[60:61]
	global_load_dword v137, v0, s[60:61]
	global_load_dword v138, v0, s[60:61]
	global_load_dword v139, v0, s[60:61]
.Lxppg_procA:
	s_lshr_b32 s64, s59, 6
	s_and_b32 s65, s59, 63
	s_mul_i32 s68, s65, 0x20000
	s_lshl_b32 s64, s64, 7
	s_add_i32 s68, s68, s64
	s_add_u32 s64, s62, s68
	s_addc_u32 s65, s63, 0
	s_waitcnt vmcnt(63)
	ds_write_b32 v6, v20 offset:0
	s_waitcnt vmcnt(62)
	ds_write_b32 v6, v21 offset:264
	s_waitcnt vmcnt(61)
	ds_write_b32 v6, v22 offset:528
	s_waitcnt vmcnt(60)
	ds_write_b32 v6, v23 offset:792
	s_waitcnt vmcnt(59)
	ds_write_b32 v6, v24 offset:1056
	s_waitcnt vmcnt(58)
	ds_write_b32 v6, v25 offset:1320
	s_waitcnt vmcnt(57)
	ds_write_b32 v6, v26 offset:1584
	s_waitcnt vmcnt(56)
	ds_write_b32 v6, v27 offset:1848
	s_waitcnt vmcnt(55)
	ds_write_b32 v6, v28 offset:2112
	s_waitcnt vmcnt(54)
	ds_write_b32 v6, v29 offset:2376
	s_waitcnt vmcnt(53)
	ds_write_b32 v6, v30 offset:2640
	s_waitcnt vmcnt(52)
	ds_write_b32 v6, v31 offset:2904
	s_waitcnt vmcnt(51)
	ds_write_b32 v6, v32 offset:3168
	s_waitcnt vmcnt(50)
	ds_write_b32 v6, v33 offset:3432
	s_waitcnt vmcnt(49)
	ds_write_b32 v6, v34 offset:3696
	s_waitcnt vmcnt(48)
	ds_write_b32 v6, v35 offset:3960
	s_waitcnt vmcnt(47)
	ds_write_b32 v6, v36 offset:4224
	s_waitcnt vmcnt(46)
	ds_write_b32 v6, v37 offset:4488
	s_waitcnt vmcnt(45)
	ds_write_b32 v6, v38 offset:4752
	s_waitcnt vmcnt(44)
	ds_write_b32 v6, v39 offset:5016
	s_waitcnt vmcnt(43)
	ds_write_b32 v6, v40 offset:5280
	s_waitcnt vmcnt(42)
	ds_write_b32 v6, v41 offset:5544
	s_waitcnt vmcnt(41)
	ds_write_b32 v6, v42 offset:5808
	s_waitcnt vmcnt(40)
	ds_write_b32 v6, v43 offset:6072
	s_waitcnt vmcnt(39)
	ds_write_b32 v6, v44 offset:6336
	s_waitcnt vmcnt(38)
	ds_write_b32 v6, v45 offset:6600
	s_waitcnt vmcnt(37)
	ds_write_b32 v6, v46 offset:6864
	s_waitcnt vmcnt(36)
	ds_write_b32 v6, v47 offset:7128
	s_waitcnt vmcnt(35)
	ds_write_b32 v6, v48 offset:7392
	s_waitcnt vmcnt(34)
	ds_write_b32 v6, v49 offset:7656
	s_waitcnt vmcnt(33)
	ds_write_b32 v6, v50 offset:7920
	s_waitcnt vmcnt(32)
	ds_write_b32 v6, v51 offset:8184
	s_waitcnt lgkmcnt(0)
	ds_read2_b32 v[60:61], v9 offset0:0 offset1:33
	ds_read2_b32 v[62:63], v9 offset0:66 offset1:99
	ds_read2_b32 v[64:65], v9 offset0:132 offset1:165
	ds_read2_b32 v[66:67], v9 offset0:198 offset1:231
	ds_read2_b32 v[68:69], v9 offset0:8 offset1:41
	ds_read2_b32 v[70:71], v9 offset0:74 offset1:107
	ds_read2_b32 v[72:73], v9 offset0:140 offset1:173
	ds_read2_b32 v[74:75], v9 offset0:206 offset1:239
	ds_read2_b32 v[76:77], v9 offset0:16 offset1:49
	ds_read2_b32 v[78:79], v9 offset0:82 offset1:115
	ds_read2_b32 v[80:81], v9 offset0:148 offset1:181
	ds_read2_b32 v[82:83], v9 offset0:214 offset1:247
	ds_read2_b32 v[84:85], v9 offset0:24 offset1:57
	ds_read2_b32 v[86:87], v9 offset0:90 offset1:123
	ds_read2_b32 v[88:89], v9 offset0:156 offset1:189
	ds_read2_b32 v[90:91], v9 offset0:222 offset1:255
	s_waitcnt lgkmcnt(12)
	v_mul_f32_e32 v60, v60, v52
	v_mul_f32_e32 v61, v61, v53
	v_mul_f32_e32 v62, v62, v54
	v_mul_f32_e32 v63, v63, v55
	v_mul_f32_e32 v64, v64, v56
	v_mul_f32_e32 v65, v65, v57
	v_mul_f32_e32 v66, v66, v58
	v_mul_f32_e32 v67, v67, v59
	v_cvt_pk_bf16_f32 v92, v60, v61
	v_cvt_pk_bf16_f32 v93, v62, v63
	v_cvt_pk_bf16_f32 v94, v64, v65
	v_cvt_pk_bf16_f32 v95, v66, v67
	global_store_dwordx4 v12, v[92:95], s[64:65]
	s_waitcnt lgkmcnt(8)
	v_mul_f32_e32 v68, v68, v52
	v_mul_f32_e32 v69, v69, v53
	v_mul_f32_e32 v70, v70, v54
	v_mul_f32_e32 v71, v71, v55
	v_mul_f32_e32 v72, v72, v56
	v_mul_f32_e32 v73, v73, v57
	v_mul_f32_e32 v74, v74, v58
	v_mul_f32_e32 v75, v75, v59
	v_cvt_pk_bf16_f32 v96, v68, v69
	v_cvt_pk_bf16_f32 v97, v70, v71
	v_cvt_pk_bf16_f32 v98, v72, v73
	v_cvt_pk_bf16_f32 v99, v74, v75
	global_store_dwordx4 v13, v[96:99], s[64:65]
	s_waitcnt lgkmcnt(4)
	v_mul_f32_e32 v76, v76, v52
	v_mul_f32_e32 v77, v77, v53
	v_mul_f32_e32 v78, v78, v54
	v_mul_f32_e32 v79, v79, v55
	v_mul_f32_e32 v80, v80, v56
	v_mul_f32_e32 v81, v81, v57
	v_mul_f32_e32 v82, v82, v58
	v_mul_f32_e32 v83, v83, v59
	v_cvt_pk_bf16_f32 v100, v76, v77
	v_cvt_pk_bf16_f32 v101, v78, v79
	v_cvt_pk_bf16_f32 v102, v80, v81
	v_cvt_pk_bf16_f32 v103, v82, v83
	global_store_dwordx4 v14, v[100:103], s[64:65]
	s_waitcnt lgkmcnt(0)
	v_mul_f32_e32 v84, v84, v52
	v_mul_f32_e32 v85, v85, v53
	v_mul_f32_e32 v86, v86, v54
	v_mul_f32_e32 v87, v87, v55
	v_mul_f32_e32 v88, v88, v56
	v_mul_f32_e32 v89, v89, v57
	v_mul_f32_e32 v90, v90, v58
	v_mul_f32_e32 v91, v91, v59
	v_cvt_pk_bf16_f32 v104, v84, v85
	v_cvt_pk_bf16_f32 v105, v86, v87
	v_cvt_pk_bf16_f32 v106, v88, v89
	v_cvt_pk_bf16_f32 v107, v90, v91
	global_store_dwordx4 v15, v[104:107], s[64:65]
	s_cmpk_lt_i32 s32, 0x800
	s_cbranch_scc0 .Lxppg_fin
; #define LAS __attribute__((address_space(3)))
; __device__ __forceinline__ unsigned cvt_pk_bf16(float lo, float hi) { unsigned r; asm volatile("v_cvt_pk_bf16_f32 %0, %1, %2" : "=v"(r) : "v"(lo), "v"(hi)); return r; }
; __device__ __forceinline__ void xpose_item(const float* src, int ld, bf16_t* dst, int K, int k0, LAS float* scr, int lane, const float* gk) {
;     if (src) {
; #pragma unroll 8
;         for (int i = 0; i < 32; ++i) { const int kk = 2 * i + (lane >> 5); scr[kk * 33 + (lane & 31)] = __builtin_nontemporal_load(src + (size_t)(k0 + kk) * ld + (lane & 31)); }
;     } else {
; #pragma unroll 8
;         for (int i = 0; i < 32; ++i) { const int kk = 2 * i + (lane >> 5); scr[kk * 33 + (lane & 31)] = 0.f; }
;     }
;     const int c = lane & 7;
;     f32x4 g0 = (f32x4){1.f, 1.f, 1.f, 1.f}, g1 = g0;
;     if (gk) { g0 = *(const f32x4*)(gk + k0 + 8 * c); g1 = *(const f32x4*)(gk + k0 + 8 * c + 4); }
;     asm volatile("s_waitcnt lgkmcnt(0)" ::: "memory");
; #pragma unroll
;     for (int j = 0; j < 4; ++j) { const int n = (lane >> 3) + 8 * j; const LAS float* s = scr + (8 * c) * 33 + n;
;         u32x4 o; o.x = cvt_pk_bf16(s[0 * 33] * g0[0], s[1 * 33] * g0[1]); o.y = cvt_pk_bf16(s[2 * 33] * g0[2], s[3 * 33] * g0[3]); o.z = cvt_pk_bf16(s[4 * 33] * g1[0], s[5 * 33] * g1[1]); o.w = cvt_pk_bf16(s[6 * 33] * g1[2], s[7 * 33] * g1[3]);
;         *(u32x4*)(dst + (size_t)n * K + k0 + 8 * c) = o; }
;     asm volatile("s_waitcnt lgkmcnt(0)" ::: "memory");
; }
; __global__ void __launch_bounds__(512) mega(Args a_byval) {
;     ...
;             it = xpose_all(a.in[27] + (size_t)lyr * D * D, nullptr, 2048, 2048, 2048, 2048, 0, (bf16_t*)(ws + (lyr ? WS_W_PG1 : WS_W_PG)), it, NGW, scr, lane, norm_ple_g + lyr * D);
	s_add_i32 s59, s32, 0x400
	s_cmpk_lt_i32 s59, 0x800
	s_cbranch_scc0 .Lxppg_dumA
	s_lshr_b32 s64, s59, 6
	s_and_b32 s65, s59, 63
	s_lshl_b32 s66, s64, 19
	s_lshl_b32 s67, s65, 7
	s_add_i32 s66, s66, s67
	s_add_u32 s66, s60, s66
	s_addc_u32 s67, s61, 0
	s_lshl_b32 s64, s64, 8
	s_mov_b32 s65, 0
	v_lshl_add_u64 v[18:19], s[64:65], 0, v[16:17]
	global_load_dwordx4 v[52:55], v[18:19], off
	global_load_dwordx4 v[56:59], v[18:19], off offset:16
	v_mov_b32_e32 v11, v5
	global_load_dword v20, v11, s[66:67] nt
	v_add_u32_e32 v11, 0x4000, v11
	global_load_dword v21, v11, s[66:67] nt
	v_add_u32_e32 v11, 0x4000, v11
	global_load_dword v22, v11, s[66:67] nt
	v_add_u32_e32 v11, 0x4000, v11
	global_load_dword v23, v11, s[66:67] nt
	v_add_u32_e32 v11, 0x4000, v11
	global_load_dword v24, v11, s[66:67] nt
	v_add_u32_e32 v11, 0x4000, v11
	global_load_dword v25, v11, s[66:67] nt
	v_add_u32_e32 v11, 0x4000, v11
	global_load_dword v26, v11, s[66:67] nt
	v_add_u32_e32 v11, 0x4000, v11
	global_load_dword v27, v11, s[66:67] nt
	v_add_u32_e32 v11, 0x4000, v11
	global_load_dword v28, v11, s[66:67] nt
	v_add_u32_e32 v11, 0x4000, v11
	global_load_dword v29, v11, s[66:67] nt
	v_add_u32_e32 v11, 0x4000, v11
	global_load_dword v30, v11, s[66:67] nt
	v_add_u32_e32 v11, 0x4000, v11
	global_load_dword v31, v11, s[66:67] nt
	v_add_u32_e32 v11, 0x4000, v11
	global_load_dword v32, v11, s[66:67] nt
	v_add_u32_e32 v11, 0x4000, v11
	global_load_dword v33, v11, s[66:67] nt
	v_add_u32_e32 v11, 0x4000, v11
	global_load_dword v34, v11, s[66:67] nt
	v_add_u32_e32 v11, 0x4000, v11
	global_load_dword v35, v11, s[66:67] nt
	v_add_u32_e32 v11, 0x4000, v11
	global_load_dword v36, v11, s[66:67] nt
	v_add_u32_e32 v11, 0x4000, v11
	global_load_dword v37, v11, s[66:67] nt
	v_add_u32_e32 v11, 0x4000, v11
	global_load_dword v38, v11, s[66:67] nt
	v_add_u32_e32 v11, 0x4000, v11
	global_load_dword v39, v11, s[66:67] nt
	v_add_u32_e32 v11, 0x4000, v11
	global_load_dword v40, v11, s[66:67] nt
	v_add_u32_e32 v11, 0x4000, v11
	global_load_dword v41, v11, s[66:67] nt
	v_add_u32_e32 v11, 0x4000, v11
	global_load_dword v42, v11, s[66:67] nt
	v_add_u32_e32 v11, 0x4000, v11
	global_load_dword v43, v11, s[66:67] nt
	v_add_u32_e32 v11, 0x4000, v11
	global_load_dword v44, v11, s[66:67] nt
	v_add_u32_e32 v11, 0x4000, v11
	global_load_dword v45, v11, s[66:67] nt
	v_add_u32_e32 v11, 0x4000, v11
	global_load_dword v46, v11, s[66:67] nt
	v_add_u32_e32 v11, 0x4000, v11
	global_load_dword v47, v11, s[66:67] nt
	v_add_u32_e32 v11, 0x4000, v11
	global_load_dword v48, v11, s[66:67] nt
	v_add_u32_e32 v11, 0x4000, v11
	global_load_dword v49, v11, s[66:67] nt
	v_add_u32_e32 v11, 0x4000, v11
	global_load_dword v50, v11, s[66:67] nt
	v_add_u32_e32 v11, 0x4000, v11
	global_load_dword v51, v11, s[66:67] nt
	s_branch .Lxppg_procB
.Lxppg_dumA:
	global_load_dwordx4 v[52:55], v[16:17], off
	global_load_dwordx4 v[56:59], v[16:17], off
	global_load_dword v20, v0, s[60:61]
	global_load_dword v21, v0, s[60:61]
	global_load_dword v22, v0, s[60:61]
	global_load_dword v23, v0, s[60:61]
	global_load_dword v24, v0, s[60:61]
	global_load_dword v25, v0, s[60:61]
	global_load_dword v26, v0, s[60:61]
	global_load_dword v27, v0, s[60:61]
	global_load_dword v28, v0, s[60:61]
	global_load_dword v29, v0, s[60:61]
	global_load_dword v30, v0, s[60:61]
	global_load_dword v31, v0, s[60:61]
	global_load_dword v32, v0, s[60:61]
	global_load_dword v33, v0, s[60:61]
	global_load_dword v34, v0, s[60:61]
	global_load_dword v35, v0, s[60:61]
	global_load_dword v36, v0, s[60:61]
	global_load_dword v37, v0, s[60:61]
	global_load_dword v38, v0, s[60:61]
	global_load_dword v39, v0, s[60:61]
	global_load_dword v40, v0, s[60:61]
	global_load_dword v41, v0, s[60:61]
	global_load_dword v42, v0, s[60:61]
	global_load_dword v43, v0, s[60:61]
	global_load_dword v44, v0, s[60:61]
	global_load_dword v45, v0, s[60:61]
	global_load_dword v46, v0, s[60:61]
	global_load_dword v47, v0, s[60:61]
	global_load_dword v48, v0, s[60:61]
	global_load_dword v49, v0, s[60:61]
	global_load_dword v50, v0, s[60:61]
	global_load_dword v51, v0, s[60:61]
; #define LAS __attribute__((address_space(3)))
; __device__ __forceinline__ unsigned cvt_pk_bf16(float lo, float hi) { unsigned r; asm volatile("v_cvt_pk_bf16_f32 %0, %1, %2" : "=v"(r) : "v"(lo), "v"(hi)); return r; }
; __device__ __forceinline__ void xpose_item(const float* src, int ld, bf16_t* dst, int K, int k0, LAS float* scr, int lane, const float* gk) {
;     if (src) {
; #pragma unroll 8
;         for (int i = 0; i < 32; ++i) { const int kk = 2 * i + (lane >> 5); scr[kk * 33 + (lane & 31)] = __builtin_nontemporal_load(src + (size_t)(k0 + kk) * ld + (lane & 31)); }
;     } else {
; #pragma unroll 8
;         for (int i = 0; i < 32; ++i) { const int kk = 2 * i + (lane >> 5); scr[kk * 33 + (lane & 31)] = 0.f; }
;     }
;     const int c = lane & 7;
;     f32x4 g0 = (f32x4){1.f, 1.f, 1.f, 1.f}, g1 = g0;
;     if (gk) { g0 = *(const f32x4*)(gk + k0 + 8 * c); g1 = *(const f32x4*)(gk + k0 + 8 * c + 4); }
;     asm volatile("s_waitcnt lgkmcnt(0)" ::: "memory");
; #pragma unroll
;     for (int j = 0; j < 4; ++j) { const int n = (lane >> 3) + 8 * j; const LAS float* s = scr + (8 * c) * 33 + n;
;         u32x4 o; o.x = cvt_pk_bf16(s[0 * 33] * g0[0], s[1 * 33] * g0[1]); o.y = cvt_pk_bf16(s[2 * 33] * g0[2], s[3 * 33] * g0[3]); o.z = cvt_pk_bf16(s[4 * 33] * g1[0], s[5 * 33] * g1[1]); o.w = cvt_pk_bf16(s[6 * 33] * g1[2], s[7 * 33] * g1[3]);
;         *(u32x4*)(dst + (size_t)n * K + k0 + 8 * c) = o; }
;     asm volatile("s_waitcnt lgkmcnt(0)" ::: "memory");
; }
; __global__ void __launch_bounds__(512) mega(Args a_byval) {
;     ...
;             it = xpose_all(a.in[27] + (size_t)lyr * D * D, nullptr, 2048, 2048, 2048, 2048, 0, (bf16_t*)(ws + (lyr ? WS_W_PG1 : WS_W_PG)), it, NGW, scr, lane, norm_ple_g + lyr * D);
.Lxppg_procB:
	s_lshr_b32 s64, s32, 6
	s_and_b32 s65, s32, 63
	s_mul_i32 s68, s65, 0x20000
	s_lshl_b32 s64, s64, 7
	s_add_i32 s68, s68, s64
	s_add_u32 s64, s62, s68
	s_addc_u32 s65, s63, 0
	s_waitcnt vmcnt(63)
	ds_write_b32 v6, v108 offset:0
	s_waitcnt vmcnt(62)
	ds_write_b32 v6, v109 offset:264
	s_waitcnt vmcnt(61)
	ds_write_b32 v6, v110 offset:528
	s_waitcnt vmcnt(60)
	ds_write_b32 v6, v111 offset:792
	s_waitcnt vmcnt(59)
	ds_write_b32 v6, v112 offset:1056
	s_waitcnt vmcnt(58)
	ds_write_b32 v6, v113 offset:1320
	s_waitcnt vmcnt(57)
	ds_write_b32 v6, v114 offset:1584
	s_waitcnt vmcnt(56)
	ds_write_b32 v6, v115 offset:1848
	s_waitcnt vmcnt(55)
	ds_write_b32 v6, v116 offset:2112
	s_waitcnt vmcnt(54)
	ds_write_b32 v6, v117 offset:2376
	s_waitcnt vmcnt(53)
	ds_write_b32 v6, v118 offset:2640
	s_waitcnt vmcnt(52)
	ds_write_b32 v6, v119 offset:2904
	s_waitcnt vmcnt(51)
	ds_write_b32 v6, v120 offset:3168
	s_waitcnt vmcnt(50)
	ds_write_b32 v6, v121 offset:3432
	s_waitcnt vmcnt(49)
	ds_write_b32 v6, v122 offset:3696
	s_waitcnt vmcnt(48)
	ds_write_b32 v6, v123 offset:3960
	s_waitcnt vmcnt(47)
	ds_write_b32 v6, v124 offset:4224
	s_waitcnt vmcnt(46)
	ds_write_b32 v6, v125 offset:4488
	s_waitcnt vmcnt(45)
	ds_write_b32 v6, v126 offset:4752
	s_waitcnt vmcnt(44)
	ds_write_b32 v6, v127 offset:5016
	s_waitcnt vmcnt(43)
	ds_write_b32 v6, v128 offset:5280
	s_waitcnt vmcnt(42)
	ds_write_b32 v6, v129 offset:5544
	s_waitcnt vmcnt(41)
	ds_write_b32 v6, v130 offset:5808
	s_waitcnt vmcnt(40)
	ds_write_b32 v6, v131 offset:6072
	s_waitcnt vmcnt(39)
	ds_write_b32 v6, v132 offset:6336
	s_waitcnt vmcnt(38)
	ds_write_b32 v6, v133 offset:6600
	s_waitcnt vmcnt(37)
	ds_write_b32 v6, v134 offset:6864
	s_waitcnt vmcnt(36)
	ds_write_b32 v6, v135 offset:7128
	s_waitcnt vmcnt(35)
	ds_write_b32 v6, v136 offset:7392
	s_waitcnt vmcnt(34)
	ds_write_b32 v6, v137 offset:7656
	s_waitcnt vmcnt(33)
	ds_write_b32 v6, v138 offset:7920
	s_waitcnt vmcnt(32)
	ds_write_b32 v6, v139 offset:8184
	s_waitcnt lgkmcnt(0)
	ds_read2_b32 v[60:61], v9 offset0:0 offset1:33
	ds_read2_b32 v[62:63], v9 offset0:66 offset1:99
	ds_read2_b32 v[64:65], v9 offset0:132 offset1:165
	ds_read2_b32 v[66:67], v9 offset0:198 offset1:231
	ds_read2_b32 v[68:69], v9 offset0:8 offset1:41
	ds_read2_b32 v[70:71], v9 offset0:74 offset1:107
	ds_read2_b32 v[72:73], v9 offset0:140 offset1:173
	ds_read2_b32 v[74:75], v9 offset0:206 offset1:239
	ds_read2_b32 v[76:77], v9 offset0:16 offset1:49
	ds_read2_b32 v[78:79], v9 offset0:82 offset1:115
	ds_read2_b32 v[80:81], v9 offset0:148 offset1:181
	ds_read2_b32 v[82:83], v9 offset0:214 offset1:247
	ds_read2_b32 v[84:85], v9 offset0:24 offset1:57
	ds_read2_b32 v[86:87], v9 offset0:90 offset1:123
	ds_read2_b32 v[88:89], v9 offset0:156 offset1:189
	ds_read2_b32 v[90:91], v9 offset0:222 offset1:255
	s_waitcnt lgkmcnt(12)
	v_mul_f32_e32 v60, v60, v160
	v_mul_f32_e32 v61, v61, v161
	v_mul_f32_e32 v62, v62, v162
	v_mul_f32_e32 v63, v63, v163
	v_mul_f32_e32 v64, v64, v164
	v_mul_f32_e32 v65, v65, v165
	v_mul_f32_e32 v66, v66, v166
	v_mul_f32_e32 v67, v67, v167
	v_cvt_pk_bf16_f32 v92, v60, v61
	v_cvt_pk_bf16_f32 v93, v62, v63
	v_cvt_pk_bf16_f32 v94, v64, v65
	v_cvt_pk_bf16_f32 v95, v66, v67
	global_store_dwordx4 v12, v[92:95], s[64:65]
	s_waitcnt lgkmcnt(8)
	v_mul_f32_e32 v68, v68, v160
	v_mul_f32_e32 v69, v69, v161
	v_mul_f32_e32 v70, v70, v162
	v_mul_f32_e32 v71, v71, v163
	v_mul_f32_e32 v72, v72, v164
	v_mul_f32_e32 v73, v73, v165
	v_mul_f32_e32 v74, v74, v166
	v_mul_f32_e32 v75, v75, v167
	v_cvt_pk_bf16_f32 v96, v68, v69
	v_cvt_pk_bf16_f32 v97, v70, v71
	v_cvt_pk_bf16_f32 v98, v72, v73
	v_cvt_pk_bf16_f32 v99, v74, v75
	global_store_dwordx4 v13, v[96:99], s[64:65]
	s_waitcnt lgkmcnt(4)
	v_mul_f32_e32 v76, v76, v160
	v_mul_f32_e32 v77, v77, v161
	v_mul_f32_e32 v78, v78, v162
	v_mul_f32_e32 v79, v79, v163
	v_mul_f32_e32 v80, v80, v164
	v_mul_f32_e32 v81, v81, v165
	v_mul_f32_e32 v82, v82, v166
	v_mul_f32_e32 v83, v83, v167
	v_cvt_pk_bf16_f32 v100, v76, v77
	v_cvt_pk_bf16_f32 v101, v78, v79
	v_cvt_pk_bf16_f32 v102, v80, v81
	v_cvt_pk_bf16_f32 v103, v82, v83
	global_store_dwordx4 v14, v[100:103], s[64:65]
	s_waitcnt lgkmcnt(0)
	v_mul_f32_e32 v84, v84, v160
	v_mul_f32_e32 v85, v85, v161
	v_mul_f32_e32 v86, v86, v162
	v_mul_f32_e32 v87, v87, v163
	v_mul_f32_e32 v88, v88, v164
	v_mul_f32_e32 v89, v89, v165
	v_mul_f32_e32 v90, v90, v166
	v_mul_f32_e32 v91, v91, v167
	v_cvt_pk_bf16_f32 v104, v84, v85
	v_cvt_pk_bf16_f32 v105, v86, v87
	v_cvt_pk_bf16_f32 v106, v88, v89
	v_cvt_pk_bf16_f32 v107, v90, v91
	global_store_dwordx4 v15, v[104:107], s[64:65]
	s_cmpk_lt_i32 s59, 0x800
	s_cbranch_scc1 .Lxppg_loop
	s_branch .Lxppg_drain

; #define LAS __attribute__((address_space(3)))
; __device__ __forceinline__ unsigned cvt_pk_bf16(float lo, float hi) { unsigned r; asm volatile("v_cvt_pk_bf16_f32 %0, %1, %2" : "=v"(r) : "v"(lo), "v"(hi)); return r; }
; __device__ __forceinline__ void xpose_item(const float* src, int ld, bf16_t* dst, int K, int k0, LAS float* scr, int lane, const float* gk) {
;     if (src) {
; #pragma unroll 8
;         for (int i = 0; i < 32; ++i) { const int kk = 2 * i + (lane >> 5); scr[kk * 33 + (lane & 31)] = __builtin_nontemporal_load(src + (size_t)(k0 + kk) * ld + (lane & 31)); }
;     } else {
; #pragma unroll 8
;         for (int i = 0; i < 32; ++i) { const int kk = 2 * i + (lane >> 5); scr[kk * 33 + (lane & 31)] = 0.f; }
;     }
;     const int c = lane & 7;
;     f32x4 g0 = (f32x4){1.f, 1.f, 1.f, 1.f}, g1 = g0;
;     if (gk) { g0 = *(const f32x4*)(gk + k0 + 8 * c); g1 = *(const f32x4*)(gk + k0 + 8 * c + 4); }
;     asm volatile("s_waitcnt lgkmcnt(0)" ::: "memory");
; #pragma unroll
;     for (int j = 0; j < 4; ++j) { const int n = (lane >> 3) + 8 * j; const LAS float* s = scr + (8 * c) * 33 + n;
;         u32x4 o; o.x = cvt_pk_bf16(s[0 * 33] * g0[0], s[1 * 33] * g0[1]); o.y = cvt_pk_bf16(s[2 * 33] * g0[2], s[3 * 33] * g0[3]); o.z = cvt_pk_bf16(s[4 * 33] * g1[0], s[5 * 33] * g1[1]); o.w = cvt_pk_bf16(s[6 * 33] * g1[2], s[7 * 33] * g1[3]);
;         *(u32x4*)(dst + (size_t)n * K + k0 + 8 * c) = o; }
;     asm volatile("s_waitcnt lgkmcnt(0)" ::: "memory");
; }
; __global__ void __launch_bounds__(512) mega(Args a_byval) {
;     ...
;             it = xpose_all(a.in[26] + (size_t)lyr * PLE * D, nullptr, 2048, 256, 2048, 2048, 0, (bf16_t*)(ws + (lyr ? WS_W_PP1 : WS_W_PP)), it, NGW, scr, lane);
.Lxppg_end:
	s_sub_i32 s59, s59, 0x800
	s_cmpk_ge_i32 s59, 0x100
	s_cbranch_scc1 .Lxppp_end
	s_load_dwordx2 s[60:61], s[92:93], 0xd0
	s_load_dwordx2 s[62:63], s[92:93], 0xe8
	v_mov_b32_e32 v10, 0x200
	v_mul_u32_u24_e32 v10, v8, v10
	v_lshl_add_u32 v12, v7, 4, v10
	v_add_u32_e32 v13, 0x1000, v12
	v_add_u32_e32 v14, 0x2000, v12
	v_add_u32_e32 v15, 0x3000, v12
	s_waitcnt lgkmcnt(0)
	s_add_u32 s60, s60, 0x200000
	s_addc_u32 s61, s61, 0
	s_add_u32 s62, s62, 0x2200000
	s_addc_u32 s63, s63, 0
	s_lshr_b32 s64, s59, 6
	s_and_b32 s65, s59, 63
	s_lshl_b32 s66, s64, 19
	s_lshl_b32 s67, s65, 7
	s_add_i32 s66, s66, s67
	s_add_u32 s66, s60, s66
	s_addc_u32 s67, s61, 0
	v_mov_b32_e32 v11, v5
	global_load_dword v20, v11, s[66:67] nt
	v_add_u32_e32 v11, 0x4000, v11
	global_load_dword v21, v11, s[66:67] nt
	v_add_u32_e32 v11, 0x4000, v11
	global_load_dword v22, v11, s[66:67] nt
	v_add_u32_e32 v11, 0x4000, v11
	global_load_dword v23, v11, s[66:67] nt
	v_add_u32_e32 v11, 0x4000, v11
	global_load_dword v24, v11, s[66:67] nt
	v_add_u32_e32 v11, 0x4000, v11
	global_load_dword v25, v11, s[66:67] nt
	v_add_u32_e32 v11, 0x4000, v11
	global_load_dword v26, v11, s[66:67] nt
	v_add_u32_e32 v11, 0x4000, v11
	global_load_dword v27, v11, s[66:67] nt
	v_add_u32_e32 v11, 0x4000, v11
	global_load_dword v28, v11, s[66:67] nt
	v_add_u32_e32 v11, 0x4000, v11
	global_load_dword v29, v11, s[66:67] nt
	v_add_u32_e32 v11, 0x4000, v11
	global_load_dword v30, v11, s[66:67] nt
	v_add_u32_e32 v11, 0x4000, v11
	global_load_dword v31, v11, s[66:67] nt
	v_add_u32_e32 v11, 0x4000, v11
	global_load_dword v32, v11, s[66:67] nt
	v_add_u32_e32 v11, 0x4000, v11
	global_load_dword v33, v11, s[66:67] nt
	v_add_u32_e32 v11, 0x4000, v11
	global_load_dword v34, v11, s[66:67] nt
	v_add_u32_e32 v11, 0x4000, v11
	global_load_dword v35, v11, s[66:67] nt
	v_add_u32_e32 v11, 0x4000, v11
	global_load_dword v36, v11, s[66:67] nt
	v_add_u32_e32 v11, 0x4000, v11
	global_load_dword v37, v11, s[66:67] nt
	v_add_u32_e32 v11, 0x4000, v11
	global_load_dword v38, v11, s[66:67] nt
	v_add_u32_e32 v11, 0x4000, v11
	global_load_dword v39, v11, s[66:67] nt
	v_add_u32_e32 v11, 0x4000, v11
	global_load_dword v40, v11, s[66:67] nt
	v_add_u32_e32 v11, 0x4000, v11
	global_load_dword v41, v11, s[66:67] nt
	v_add_u32_e32 v11, 0x4000, v11
	global_load_dword v42, v11, s[66:67] nt
	v_add_u32_e32 v11, 0x4000, v11
	global_load_dword v43, v11, s[66:67] nt
	v_add_u32_e32 v11, 0x4000, v11
	global_load_dword v44, v11, s[66:67] nt
	v_add_u32_e32 v11, 0x4000, v11
	global_load_dword v45, v11, s[66:67] nt
	v_add_u32_e32 v11, 0x4000, v11
	global_load_dword v46, v11, s[66:67] nt
	v_add_u32_e32 v11, 0x4000, v11
	global_load_dword v47, v11, s[66:67] nt
	v_add_u32_e32 v11, 0x4000, v11
	global_load_dword v48, v11, s[66:67] nt
	v_add_u32_e32 v11, 0x4000, v11
	global_load_dword v49, v11, s[66:67] nt
	v_add_u32_e32 v11, 0x4000, v11
	global_load_dword v50, v11, s[66:67] nt
	v_add_u32_e32 v11, 0x4000, v11
	global_load_dword v51, v11, s[66:67] nt
.Lxppp_loop:
	s_add_i32 s32, s59, 0x400
	s_cmpk_lt_i32 s32, 0x100
	s_cbranch_scc0 .Lxppp_dumB
	s_lshr_b32 s64, s32, 6
	s_and_b32 s65, s32, 63
	s_lshl_b32 s66, s64, 19
	s_lshl_b32 s67, s65, 7
	s_add_i32 s66, s66, s67
	s_add_u32 s66, s60, s66
	s_addc_u32 s67, s61, 0
	v_mov_b32_e32 v11, v5
	global_load_dword v108, v11, s[66:67] nt
	v_add_u32_e32 v11, 0x4000, v11
	global_load_dword v109, v11, s[66:67] nt
	v_add_u32_e32 v11, 0x4000, v11
	global_load_dword v110, v11, s[66:67] nt
	v_add_u32_e32 v11, 0x4000, v11
	global_load_dword v111, v11, s[66:67] nt
	v_add_u32_e32 v11, 0x4000, v11
	global_load_dword v112, v11, s[66:67] nt
	v_add_u32_e32 v11, 0x4000, v11
	global_load_dword v113, v11, s[66:67] nt
	v_add_u32_e32 v11, 0x4000, v11
	global_load_dword v114, v11, s[66:67] nt
	v_add_u32_e32 v11, 0x4000, v11
	global_load_dword v115, v11, s[66:67] nt
	v_add_u32_e32 v11, 0x4000, v11
	global_load_dword v116, v11, s[66:67] nt
	v_add_u32_e32 v11, 0x4000, v11
	global_load_dword v117, v11, s[66:67] nt
	v_add_u32_e32 v11, 0x4000, v11
	global_load_dword v118, v11, s[66:67] nt
	v_add_u32_e32 v11, 0x4000, v11
	global_load_dword v119, v11, s[66:67] nt
	v_add_u32_e32 v11, 0x4000, v11
	global_load_dword v120, v11, s[66:67] nt
	v_add_u32_e32 v11, 0x4000, v11
	global_load_dword v121, v11, s[66:67] nt
	v_add_u32_e32 v11, 0x4000, v11
	global_load_dword v122, v11, s[66:67] nt
	v_add_u32_e32 v11, 0x4000, v11
	global_load_dword v123, v11, s[66:67] nt
	v_add_u32_e32 v11, 0x4000, v11
	global_load_dword v124, v11, s[66:67] nt
	v_add_u32_e32 v11, 0x4000, v11
	global_load_dword v125, v11, s[66:67] nt
	v_add_u32_e32 v11, 0x4000, v11
	global_load_dword v126, v11, s[66:67] nt
	v_add_u32_e32 v11, 0x4000, v11
	global_load_dword v127, v11, s[66:67] nt
	v_add_u32_e32 v11, 0x4000, v11
	global_load_dword v128, v11, s[66:67] nt
	v_add_u32_e32 v11, 0x4000, v11
	global_load_dword v129, v11, s[66:67] nt
	v_add_u32_e32 v11, 0x4000, v11
	global_load_dword v130, v11, s[66:67] nt
	v_add_u32_e32 v11, 0x4000, v11
	global_load_dword v131, v11, s[66:67] nt
	v_add_u32_e32 v11, 0x4000, v11
	global_load_dword v132, v11, s[66:67] nt
	v_add_u32_e32 v11, 0x4000, v11
	global_load_dword v133, v11, s[66:67] nt
	v_add_u32_e32 v11, 0x4000, v11
	global_load_dword v134, v11, s[66:67] nt
	v_add_u32_e32 v11, 0x4000, v11
	global_load_dword v135, v11, s[66:67] nt
	v_add_u32_e32 v11, 0x4000, v11
	global_load_dword v136, v11, s[66:67] nt
	v_add_u32_e32 v11, 0x4000, v11
	global_load_dword v137, v11, s[66:67] nt
	v_add_u32_e32 v11, 0x4000, v11
	global_load_dword v138, v11, s[66:67] nt
	v_add_u32_e32 v11, 0x4000, v11
	global_load_dword v139, v11, s[66:67] nt
	s_branch .Lxppp_procA

; #define LAS __attribute__((address_space(3)))
; __device__ __forceinline__ unsigned cvt_pk_bf16(float lo, float hi) { unsigned r; asm volatile("v_cvt_pk_bf16_f32 %0, %1, %2" : "=v"(r) : "v"(lo), "v"(hi)); return r; }
; __device__ __forceinline__ void xpose_item(const float* src, int ld, bf16_t* dst, int K, int k0, LAS float* scr, int lane, const float* gk) {
;     if (src) {
; #pragma unroll 8
;         for (int i = 0; i < 32; ++i) { const int kk = 2 * i + (lane >> 5); scr[kk * 33 + (lane & 31)] = __builtin_nontemporal_load(src + (size_t)(k0 + kk) * ld + (lane & 31)); }
;     } else {
; #pragma unroll 8
;         for (int i = 0; i < 32; ++i) { const int kk = 2 * i + (lane >> 5); scr[kk * 33 + (lane & 31)] = 0.f; }
;     }
;     const int c = lane & 7;
;     f32x4 g0 = (f32x4){1.f, 1.f, 1.f, 1.f}, g1 = g0;
;     if (gk) { g0 = *(const f32x4*)(gk + k0 + 8 * c); g1 = *(const f32x4*)(gk + k0 + 8 * c + 4); }
;     asm volatile("s_waitcnt lgkmcnt(0)" ::: "memory");
; #pragma unroll
;     for (int j = 0; j < 4; ++j) { const int n = (lane >> 3) + 8 * j; const LAS float* s = scr + (8 * c) * 33 + n;
;         u32x4 o; o.x = cvt_pk_bf16(s[0 * 33] * g0[0], s[1 * 33] * g0[1]); o.y = cvt_pk_bf16(s[2 * 33] * g0[2], s[3 * 33] * g0[3]); o.z = cvt_pk_bf16(s[4 * 33] * g1[0], s[5 * 33] * g1[1]); o.w = cvt_pk_bf16(s[6 * 33] * g1[2], s[7 * 33] * g1[3]);
;         *(u32x4*)(dst + (size_t)n * K + k0 + 8 * c) = o; }
;     asm volatile("s_waitcnt lgkmcnt(0)" ::: "memory");
; }
; __global__ void __launch_bounds__(512) mega(Args a_byval) {
;     ...
;             it = xpose_all(a.in[26] + (size_t)lyr * PLE * D, nullptr, 2048, 256, 2048, 2048, 0, (bf16_t*)(ws + (lyr ? WS_W_PP1 : WS_W_PP)), it, NGW, scr, lane);
.Lxppp_procA:
	s_lshr_b32 s64, s59, 6
	s_and_b32 s65, s59, 63
	s_mul_i32 s68, s65, 0x4000
	s_lshl_b32 s64, s64, 7
	s_add_i32 s68, s68, s64
	s_add_u32 s64, s62, s68
	s_addc_u32 s65, s63, 0
	s_waitcnt vmcnt(63)
	ds_write_b32 v6, v20 offset:0
	s_waitcnt vmcnt(62)
	ds_write_b32 v6, v21 offset:264
	s_waitcnt vmcnt(61)
	ds_write_b32 v6, v22 offset:528
	s_waitcnt vmcnt(60)
	ds_write_b32 v6, v23 offset:792
	s_waitcnt vmcnt(59)
	ds_write_b32 v6, v24 offset:1056
	s_waitcnt vmcnt(58)
	ds_write_b32 v6, v25 offset:1320
	s_waitcnt vmcnt(57)
	ds_write_b32 v6, v26 offset:1584
	s_waitcnt vmcnt(56)
	ds_write_b32 v6, v27 offset:1848
	s_waitcnt vmcnt(55)
	ds_write_b32 v6, v28 offset:2112
	s_waitcnt vmcnt(54)
	ds_write_b32 v6, v29 offset:2376
	s_waitcnt vmcnt(53)
	ds_write_b32 v6, v30 offset:2640
	s_waitcnt vmcnt(52)
	ds_write_b32 v6, v31 offset:2904
	s_waitcnt vmcnt(51)
	ds_write_b32 v6, v32 offset:3168
	s_waitcnt vmcnt(50)
	ds_write_b32 v6, v33 offset:3432
	s_waitcnt vmcnt(49)
	ds_write_b32 v6, v34 offset:3696
	s_waitcnt vmcnt(48)
	ds_write_b32 v6, v35 offset:3960
	s_waitcnt vmcnt(47)
	ds_write_b32 v6, v36 offset:4224
	s_waitcnt vmcnt(46)
	ds_write_b32 v6, v37 offset:4488
	s_waitcnt vmcnt(45)
	ds_write_b32 v6, v38 offset:4752
	s_waitcnt vmcnt(44)
	ds_write_b32 v6, v39 offset:5016
	s_waitcnt vmcnt(43)
	ds_write_b32 v6, v40 offset:5280
	s_waitcnt vmcnt(42)
	ds_write_b32 v6, v41 offset:5544
	s_waitcnt vmcnt(41)
	ds_write_b32 v6, v42 offset:5808
	s_waitcnt vmcnt(40)
	ds_write_b32 v6, v43 offset:6072
	s_waitcnt vmcnt(39)
	ds_write_b32 v6, v44 offset:6336
	s_waitcnt vmcnt(38)
	ds_write_b32 v6, v45 offset:6600
	s_waitcnt vmcnt(37)
	ds_write_b32 v6, v46 offset:6864
	s_waitcnt vmcnt(36)
	ds_write_b32 v6, v47 offset:7128
	s_waitcnt vmcnt(35)
	ds_write_b32 v6, v48 offset:7392
	s_waitcnt vmcnt(34)
	ds_write_b32 v6, v49 offset:7656
	s_waitcnt vmcnt(33)
	ds_write_b32 v6, v50 offset:7920
	s_waitcnt vmcnt(32)
	ds_write_b32 v6, v51 offset:8184
	s_waitcnt lgkmcnt(0)
	ds_read2_b32 v[60:61], v9 offset0:0 offset1:33
	ds_read2_b32 v[62:63], v9 offset0:66 offset1:99
	ds_read2_b32 v[64:65], v9 offset0:132 offset1:165
	ds_read2_b32 v[66:67], v9 offset0:198 offset1:231
	ds_read2_b32 v[68:69], v9 offset0:8 offset1:41
	ds_read2_b32 v[70:71], v9 offset0:74 offset1:107
	ds_read2_b32 v[72:73], v9 offset0:140 offset1:173
	ds_read2_b32 v[74:75], v9 offset0:206 offset1:239
	ds_read2_b32 v[76:77], v9 offset0:16 offset1:49
	ds_read2_b32 v[78:79], v9 offset0:82 offset1:115
	ds_read2_b32 v[80:81], v9 offset0:148 offset1:181
	ds_read2_b32 v[82:83], v9 offset0:214 offset1:247
	ds_read2_b32 v[84:85], v9 offset0:24 offset1:57
	ds_read2_b32 v[86:87], v9 offset0:90 offset1:123
	ds_read2_b32 v[88:89], v9 offset0:156 offset1:189
	ds_read2_b32 v[90:91], v9 offset0:222 offset1:255
	s_waitcnt lgkmcnt(12)
	v_cvt_pk_bf16_f32 v92, v60, v61
	v_cvt_pk_bf16_f32 v93, v62, v63
	v_cvt_pk_bf16_f32 v94, v64, v65
	v_cvt_pk_bf16_f32 v95, v66, v67
	global_store_dwordx4 v12, v[92:95], s[64:65]
	s_waitcnt lgkmcnt(8)
	v_cvt_pk_bf16_f32 v96, v68, v69
	v_cvt_pk_bf16_f32 v97, v70, v71
	v_cvt_pk_bf16_f32 v98, v72, v73
	v_cvt_pk_bf16_f32 v99, v74, v75
	global_store_dwordx4 v13, v[96:99], s[64:65]
	s_waitcnt lgkmcnt(4)
	v_cvt_pk_bf16_f32 v100, v76, v77
	v_cvt_pk_bf16_f32 v101, v78, v79
	v_cvt_pk_bf16_f32 v102, v80, v81
	v_cvt_pk_bf16_f32 v103, v82, v83
	global_store_dwordx4 v14, v[100:103], s[64:65]
	s_waitcnt lgkmcnt(0)
	v_cvt_pk_bf16_f32 v104, v84, v85
	v_cvt_pk_bf16_f32 v105, v86, v87
	v_cvt_pk_bf16_f32 v106, v88, v89
	v_cvt_pk_bf16_f32 v107, v90, v91
	global_store_dwordx4 v15, v[104:107], s[64:65]
	s_cmpk_lt_i32 s32, 0x100
	s_cbranch_scc0 .Lxppp_fin
	s_add_i32 s59, s32, 0x400
	s_cmpk_lt_i32 s59, 0x100
	s_cbranch_scc0 .Lxppp_dumA
	s_lshr_b32 s64, s59, 6
	s_and_b32 s65, s59, 63
	s_lshl_b32 s66, s64, 19
	s_lshl_b32 s67, s65, 7
	s_add_i32 s66, s66, s67
	s_add_u32 s66, s60, s66
	s_addc_u32 s67, s61, 0
	v_mov_b32_e32 v11, v5
	global_load_dword v20, v11, s[66:67] nt
	v_add_u32_e32 v11, 0x4000, v11
	global_load_dword v21, v11, s[66:67] nt
	v_add_u32_e32 v11, 0x4000, v11
	global_load_dword v22, v11, s[66:67] nt
	v_add_u32_e32 v11, 0x4000, v11
	global_load_dword v23, v11, s[66:67] nt
	v_add_u32_e32 v11, 0x4000, v11
	global_load_dword v24, v11, s[66:67] nt
	v_add_u32_e32 v11, 0x4000, v11
	global_load_dword v25, v11, s[66:67] nt
	v_add_u32_e32 v11, 0x4000, v11
	global_load_dword v26, v11, s[66:67] nt
	v_add_u32_e32 v11, 0x4000, v11
	global_load_dword v27, v11, s[66:67] nt
	v_add_u32_e32 v11, 0x4000, v11
	global_load_dword v28, v11, s[66:67] nt
	v_add_u32_e32 v11, 0x4000, v11
	global_load_dword v29, v11, s[66:67] nt
	v_add_u32_e32 v11, 0x4000, v11
	global_load_dword v30, v11, s[66:67] nt
	v_add_u32_e32 v11, 0x4000, v11
	global_load_dword v31, v11, s[66:67] nt
	v_add_u32_e32 v11, 0x4000, v11
	global_load_dword v32, v11, s[66:67] nt
	v_add_u32_e32 v11, 0x4000, v11
	global_load_dword v33, v11, s[66:67] nt
	v_add_u32_e32 v11, 0x4000, v11
	global_load_dword v34, v11, s[66:67] nt
	v_add_u32_e32 v11, 0x4000, v11
	global_load_dword v35, v11, s[66:67] nt
	v_add_u32_e32 v11, 0x4000, v11
	global_load_dword v36, v11, s[66:67] nt
	v_add_u32_e32 v11, 0x4000, v11
	global_load_dword v37, v11, s[66:67] nt
	v_add_u32_e32 v11, 0x4000, v11
	global_load_dword v38, v11, s[66:67] nt
	v_add_u32_e32 v11, 0x4000, v11
	global_load_dword v39, v11, s[66:67] nt
	v_add_u32_e32 v11, 0x4000, v11
	global_load_dword v40, v11, s[66:67] nt
	v_add_u32_e32 v11, 0x4000, v11
	global_load_dword v41, v11, s[66:67] nt
	v_add_u32_e32 v11, 0x4000, v11
	global_load_dword v42, v11, s[66:67] nt
	v_add_u32_e32 v11, 0x4000, v11
	global_load_dword v43, v11, s[66:67] nt
	v_add_u32_e32 v11, 0x4000, v11
	global_load_dword v44, v11, s[66:67] nt
	v_add_u32_e32 v11, 0x4000, v11
	global_load_dword v45, v11, s[66:67] nt
	v_add_u32_e32 v11, 0x4000, v11
	global_load_dword v46, v11, s[66:67] nt
	v_add_u32_e32 v11, 0x4000, v11
	global_load_dword v47, v11, s[66:67] nt
	v_add_u32_e32 v11, 0x4000, v11
	global_load_dword v48, v11, s[66:67] nt
	v_add_u32_e32 v11, 0x4000, v11
	global_load_dword v49, v11, s[66:67] nt
	v_add_u32_e32 v11, 0x4000, v11
	global_load_dword v50, v11, s[66:67] nt
	v_add_u32_e32 v11, 0x4000, v11
	global_load_dword v51, v11, s[66:67] nt
	s_branch .Lxppp_procB

; #define LAS __attribute__((address_space(3)))
; __device__ __forceinline__ unsigned cvt_pk_bf16(float lo, float hi) { unsigned r; asm volatile("v_cvt_pk_bf16_f32 %0, %1, %2" : "=v"(r) : "v"(lo), "v"(hi)); return r; }
; __device__ __forceinline__ void xpose_item(const float* src, int ld, bf16_t* dst, int K, int k0, LAS float* scr, int lane, const float* gk) {
;     if (src) {
; #pragma unroll 8
;         for (int i = 0; i < 32; ++i) { const int kk = 2 * i + (lane >> 5); scr[kk * 33 + (lane & 31)] = __builtin_nontemporal_load(src + (size_t)(k0 + kk) * ld + (lane & 31)); }
;     } else {
; #pragma unroll 8
;         for (int i = 0; i < 32; ++i) { const int kk = 2 * i + (lane >> 5); scr[kk * 33 + (lane & 31)] = 0.f; }
;     }
;     const int c = lane & 7;
;     f32x4 g0 = (f32x4){1.f, 1.f, 1.f, 1.f}, g1 = g0;
;     if (gk) { g0 = *(const f32x4*)(gk + k0 + 8 * c); g1 = *(const f32x4*)(gk + k0 + 8 * c + 4); }
;     asm volatile("s_waitcnt lgkmcnt(0)" ::: "memory");
; #pragma unroll
;     for (int j = 0; j < 4; ++j) { const int n = (lane >> 3) + 8 * j; const LAS float* s = scr + (8 * c) * 33 + n;
;         u32x4 o; o.x = cvt_pk_bf16(s[0 * 33] * g0[0], s[1 * 33] * g0[1]); o.y = cvt_pk_bf16(s[2 * 33] * g0[2], s[3 * 33] * g0[3]); o.z = cvt_pk_bf16(s[4 * 33] * g1[0], s[5 * 33] * g1[1]); o.w = cvt_pk_bf16(s[6 * 33] * g1[2], s[7 * 33] * g1[3]);
;         *(u32x4*)(dst + (size_t)n * K + k0 + 8 * c) = o; }
;     asm volatile("s_waitcnt lgkmcnt(0)" ::: "memory");
; }
; __global__ void __launch_bounds__(512) mega(Args a_byval) {
;     ...
;             it = xpose_all(a.in[26] + (size_t)lyr * PLE * D, nullptr, 2048, 256, 2048, 2048, 0, (bf16_t*)(ws + (lyr ? WS_W_PP1 : WS_W_PP)), it, NGW, scr, lane);
.Lxppp_procB:
	s_lshr_b32 s64, s32, 6
	s_and_b32 s65, s32, 63
	s_mul_i32 s68, s65, 0x4000
	s_lshl_b32 s64, s64, 7
	s_add_i32 s68, s68, s64
	s_add_u32 s64, s62, s68
	s_addc_u32 s65, s63, 0
	s_waitcnt vmcnt(63)
	ds_write_b32 v6, v108 offset:0
	s_waitcnt vmcnt(62)
	ds_write_b32 v6, v109 offset:264
	s_waitcnt vmcnt(61)
	ds_write_b32 v6, v110 offset:528
	s_waitcnt vmcnt(60)
	ds_write_b32 v6, v111 offset:792
	s_waitcnt vmcnt(59)
	ds_write_b32 v6, v112 offset:1056
	s_waitcnt vmcnt(58)
	ds_write_b32 v6, v113 offset:1320
	s_waitcnt vmcnt(57)
	ds_write_b32 v6, v114 offset:1584
	s_waitcnt vmcnt(56)
	ds_write_b32 v6, v115 offset:1848
	s_waitcnt vmcnt(55)
	ds_write_b32 v6, v116 offset:2112
	s_waitcnt vmcnt(54)
	ds_write_b32 v6, v117 offset:2376
	s_waitcnt vmcnt(53)
	ds_write_b32 v6, v118 offset:2640
	s_waitcnt vmcnt(52)
	ds_write_b32 v6, v119 offset:2904
	s_waitcnt vmcnt(51)
	ds_write_b32 v6, v120 offset:3168
	s_waitcnt vmcnt(50)
	ds_write_b32 v6, v121 offset:3432
	s_waitcnt vmcnt(49)
	ds_write_b32 v6, v122 offset:3696
	s_waitcnt vmcnt(48)
	ds_write_b32 v6, v123 offset:3960
	s_waitcnt vmcnt(47)
	ds_write_b32 v6, v124 offset:4224
	s_waitcnt vmcnt(46)
	ds_write_b32 v6, v125 offset:4488
	s_waitcnt vmcnt(45)
	ds_write_b32 v6, v126 offset:4752
	s_waitcnt vmcnt(44)
	ds_write_b32 v6, v127 offset:5016
	s_waitcnt vmcnt(43)
	ds_write_b32 v6, v128 offset:5280
	s_waitcnt vmcnt(42)
	ds_write_b32 v6, v129 offset:5544
	s_waitcnt vmcnt(41)
	ds_write_b32 v6, v130 offset:5808
	s_waitcnt vmcnt(40)
	ds_write_b32 v6, v131 offset:6072
	s_waitcnt vmcnt(39)
	ds_write_b32 v6, v132 offset:6336
	s_waitcnt vmcnt(38)
	ds_write_b32 v6, v133 offset:6600
	s_waitcnt vmcnt(37)
	ds_write_b32 v6, v134 offset:6864
	s_waitcnt vmcnt(36)
	ds_write_b32 v6, v135 offset:7128
	s_waitcnt vmcnt(35)
	ds_write_b32 v6, v136 offset:7392
	s_waitcnt vmcnt(34)
	ds_write_b32 v6, v137 offset:7656
	s_waitcnt vmcnt(33)
	ds_write_b32 v6, v138 offset:7920
	s_waitcnt vmcnt(32)
	ds_write_b32 v6, v139 offset:8184
	s_waitcnt lgkmcnt(0)
	ds_read2_b32 v[60:61], v9 offset0:0 offset1:33
	ds_read2_b32 v[62:63], v9 offset0:66 offset1:99
	ds_read2_b32 v[64:65], v9 offset0:132 offset1:165
	ds_read2_b32 v[66:67], v9 offset0:198 offset1:231
	ds_read2_b32 v[68:69], v9 offset0:8 offset1:41
	ds_read2_b32 v[70:71], v9 offset0:74 offset1:107
	ds_read2_b32 v[72:73], v9 offset0:140 offset1:173
	ds_read2_b32 v[74:75], v9 offset0:206 offset1:239
	ds_read2_b32 v[76:77], v9 offset0:16 offset1:49
	ds_read2_b32 v[78:79], v9 offset0:82 offset1:115
	ds_read2_b32 v[80:81], v9 offset0:148 offset1:181
	ds_read2_b32 v[82:83], v9 offset0:214 offset1:247
	ds_read2_b32 v[84:85], v9 offset0:24 offset1:57
	ds_read2_b32 v[86:87], v9 offset0:90 offset1:123
	ds_read2_b32 v[88:89], v9 offset0:156 offset1:189
	ds_read2_b32 v[90:91], v9 offset0:222 offset1:255
	s_waitcnt lgkmcnt(12)
	v_cvt_pk_bf16_f32 v92, v60, v61
	v_cvt_pk_bf16_f32 v93, v62, v63
	v_cvt_pk_bf16_f32 v94, v64, v65
	v_cvt_pk_bf16_f32 v95, v66, v67
	global_store_dwordx4 v12, v[92:95], s[64:65]
	s_waitcnt lgkmcnt(8)
	v_cvt_pk_bf16_f32 v96, v68, v69
	v_cvt_pk_bf16_f32 v97, v70, v71
	v_cvt_pk_bf16_f32 v98, v72, v73
	v_cvt_pk_bf16_f32 v99, v74, v75
	global_store_dwordx4 v13, v[96:99], s[64:65]
	s_waitcnt lgkmcnt(4)
	v_cvt_pk_bf16_f32 v100, v76, v77
	v_cvt_pk_bf16_f32 v101, v78, v79
	v_cvt_pk_bf16_f32 v102, v80, v81
	v_cvt_pk_bf16_f32 v103, v82, v83
	global_store_dwordx4 v14, v[100:103], s[64:65]
	s_waitcnt lgkmcnt(0)
	v_cvt_pk_bf16_f32 v104, v84, v85
	v_cvt_pk_bf16_f32 v105, v86, v87
	v_cvt_pk_bf16_f32 v106, v88, v89
	v_cvt_pk_bf16_f32 v107, v90, v91
	global_store_dwordx4 v15, v[104:107], s[64:65]
	s_cmpk_lt_i32 s59, 0x100
	s_cbranch_scc1 .Lxppp_loop
	s_branch .Lxppp_drain

; __device__ __forceinline__ int xpose_all(const float* src, const float* src2, int ld, int K, int ndst, int nsrc, int mode, bf16_t* dst, int it, int NGW, LAS float* scr, int lane, const float* gvec = nullptr) {
;     ...
;     return it - nitems;
.Lxppp_end:
	s_sub_i32 s59, s59, 0x100

; #define LAS __attribute__((address_space(3)))
; __device__ __forceinline__ int xpose_all(const float* src, const float* src2, int ld, int K, int ndst, int nsrc, int mode, bf16_t* dst, int it, int NGW, LAS float* scr, int lane, const float* gvec = nullptr) {
;     const int nblk = ndst / 32, nitems = (K / 64) * nblk;
;     for (; it < nitems; it += NGW) {
; __global__ void __launch_bounds__(512) mega(Args a_byval) {
;     ...
;                 it = xpose_all(a.in[22], nullptr, 2048, 4096, 2048, 2048, 0, (bf16_t*)(ws + WS_WB_OUT), it, NGW, scr, lane);
.LBB0_634:
	s_add_i32 s12, s14, 0xffffd7c0
	v_readlane_b32 vcc_lo, v255, 5
	s_cmpk_lg_i32 vcc_lo, 0x100
	s_cbranch_scc1 .Lxs634
	s_addk_i32 s12, 0x1000
	s_branch .LBB0_644
.Lxs634:
	s_cmpk_gt_u32 s12, 0xfff
	s_cbranch_scc1 .LBB0_644
	s_load_dwordx2 s[2:3], s[92:93], 0xb0
	s_waitcnt lgkmcnt(0)
	s_add_u32 s13, s38, 0xad00000
	v_lshlrev_b32_e32 v1, 2, v212
	v_lshrrev_b32_e32 v5, 3, v211
	s_addc_u32 s14, s39, 0
	v_lshrrev_b32_e32 v2, 5, v211
	v_and_b32_e32 v8, 0x7c, v1
	v_and_b32_e32 v1, 7, v212
	v_lshlrev_b32_e32 v3, 2, v5
	v_lshlrev_b32_e32 v12, 12, v5
	v_mov_b32_e32 v5, s26
	v_lshlrev_b32_e32 v10, 3, v1
	v_mul_u32_u24_e32 v1, 0x420, v1
	v_or_b32_e32 v14, 0x8000, v12
	v_or_b32_e32 v16, 0x10000, v12
	v_or_b32_e32 v18, 0x18000, v12
	s_cmp_lg_u64 s[2:3], 0
	v_mov_b32_e32 v9, v0
	v_mad_u32_u24 v5, v2, s33, v5
	v_add_u32_e32 v4, s27, v8
	v_add3_u32 v3, s27, v1, v3
	s_cselect_b64 s[0:1], -1, 0
	v_lshl_add_u64 v[6:7], s[2:3], 0, v[8:9]
	v_mov_b32_e32 v1, v2
	v_add3_u32 v5, v5, v8, 0
	v_lshlrev_b32_e32 v8, 1, v10
	v_lshlrev_b32_e32 v10, 1, v12
	v_lshlrev_b32_e32 v12, 1, v14
	v_lshlrev_b32_e32 v14, 1, v16
	v_lshlrev_b32_e32 v16, 1, v18
	s_branch .LBB0_637

; #define LAS __attribute__((address_space(3)))
; __device__ __forceinline__ int xpose_all(const float* src, const float* src2, int ld, int K, int ndst, int nsrc, int mode, bf16_t* dst, int it, int NGW, LAS float* scr, int lane, const float* gvec = nullptr) {
;     const int nblk = ndst / 32, nitems = (K / 64) * nblk;
;     for (; it < nitems; it += NGW) {
; __global__ void __launch_bounds__(512) mega(Args a_byval) {
;     ...
;             it = xpose_all(a.in[27] + (size_t)lyr * D * D, nullptr, 2048, 2048, 2048, 2048, 0, (bf16_t*)(ws + (lyr ? WS_W_PG1 : WS_W_PG)), it, NGW, scr, lane, norm_ple_g + lyr * D);
.LBB0_669:
	s_addk_i32 s11, 0xea00
	s_cmp_lg_u32 s76, 12
	s_cbranch_scc1 .Lxs669
	v_readlane_b32 vcc_lo, v255, 5
	s_cmpk_lg_i32 vcc_lo, 0x100
	s_cbranch_scc1 .Lxs669
	s_addk_i32 s11, 0x800
	s_branch .LBB0_683
.Lxs669:
	s_cmpk_gt_u32 s11, 0x7ff
	s_cbranch_scc1 .LBB0_683
	s_load_dwordx2 s[2:3], s[92:93], 0xd8
	s_add_u32 s18, s38, s14
	s_addc_u32 s19, s39, s15
	s_lshl_b32 s0, s12, 13
	v_readlane_b32 s20, v254, 53
	s_waitcnt lgkmcnt(0)
	s_add_u32 s14, s2, s0
	v_readlane_b32 s21, v254, 54
	s_addc_u32 s15, s3, 0
	s_lshl_b32 s0, s12, 2
	s_mov_b64 s[16:17], s[20:21]
	v_lshlrev_b32_e32 v1, 2, v212
	s_add_u32 s12, s16, s0
	v_and_b32_e32 v2, 0x7c, v1
	v_and_b32_e32 v1, 7, v212
	s_addc_u32 s13, s17, 0
	v_lshlrev_b32_e32 v6, 5, v1
	v_mov_b32_e32 v7, v0
	v_lshrrev_b32_e32 v3, 3, v211
	v_lshl_add_u64 v[14:15], s[12:13], 0, v[6:7]
	v_lshlrev_b32_e32 v5, 2, v3
	v_lshlrev_b32_e32 v6, 11, v3
	v_mov_b32_e32 v3, v0
	v_lshrrev_b32_e32 v10, 5, v211
	s_cmp_lg_u64 s[20:21], 0
	v_lshl_add_u64 v[16:17], s[14:15], 0, v[2:3]
	v_mov_b32_e32 v3, s26
	s_cselect_b64 s[0:1], -1, 0
	v_lshlrev_b32_e32 v4, 3, v1
	v_mul_u32_u24_e32 v1, 0x420, v1
	v_or_b32_e32 v8, 0x4000, v6
	v_or_b32_e32 v24, 0x8000, v6
	v_or_b32_e32 v26, 0xc000, v6
	s_cmp_lg_u64 s[2:3], 0
	v_mad_u32_u24 v3, v10, s33, v3
	v_add_u32_e32 v12, s27, v2
	v_add3_u32 v11, s27, v1, v5
	s_cselect_b64 s[2:3], -1, 0
	v_mov_b32_e32 v1, v10
	v_add3_u32 v13, v3, v2, 0
	v_lshlrev_b32_e32 v18, 1, v4
	v_lshlrev_b32_e32 v20, 1, v6
	v_lshlrev_b32_e32 v22, 1, v8
	v_lshlrev_b32_e32 v24, 1, v24
	v_lshlrev_b32_e32 v26, 1, v26
	v_readlane_b32 s22, v254, 55
	v_readlane_b32 s23, v254, 56
	s_branch .LBB0_674

; #define LAS __attribute__((address_space(3)))
; __device__ __forceinline__ int xpose_all(const float* src, const float* src2, int ld, int K, int ndst, int nsrc, int mode, bf16_t* dst, int it, int NGW, LAS float* scr, int lane, const float* gvec = nullptr) {
;     const int nblk = ndst / 32, nitems = (K / 64) * nblk;
;     for (; it < nitems; it += NGW) {
; __global__ void __launch_bounds__(512) mega(Args a_byval) {
;     ...
;             it = xpose_all(a.in[26] + (size_t)lyr * PLE * D, nullptr, 2048, 256, 2048, 2048, 0, (bf16_t*)(ws + (lyr ? WS_W_PP1 : WS_W_PP)), it, NGW, scr, lane);
.LBB0_683:
	s_add_i32 s12, s11, 0xfffff800
	s_cmp_lg_u32 s76, 12
	s_cbranch_scc1 .Lxs683
	v_readlane_b32 vcc_lo, v255, 5
	s_cmpk_lg_i32 vcc_lo, 0x100
	s_cbranch_scc1 .Lxs683
	s_addk_i32 s12, 0x100
	s_branch .LBB0_693
.Lxs683:
	s_cmpk_gt_u32 s12, 0xff
	s_cbranch_scc1 .LBB0_693
	s_load_dwordx2 s[0:1], s[92:93], 0xd0
	s_add_u32 s13, s38, s8
	s_addc_u32 s14, s39, s9
	s_lshl_b32 s2, s10, 2
	v_lshlrev_b32_e32 v1, 2, v212
	s_waitcnt lgkmcnt(0)
	s_add_u32 s2, s0, s2
	v_lshrrev_b32_e32 v5, 3, v211
	v_lshrrev_b32_e32 v2, 5, v211
	s_addc_u32 s3, s1, 0
	v_and_b32_e32 v8, 0x7c, v1
	v_and_b32_e32 v1, 7, v212
	v_lshlrev_b32_e32 v3, 2, v5
	v_lshlrev_b32_e32 v12, 8, v5
	v_mov_b32_e32 v5, s26
	v_lshlrev_b32_e32 v10, 3, v1
	v_mul_u32_u24_e32 v1, 0x420, v1
	v_or_b32_e32 v14, 0x800, v12
	v_or_b32_e32 v16, 0x1000, v12
	v_or_b32_e32 v18, 0x1800, v12
	s_cmp_lg_u64 s[0:1], 0
	v_mov_b32_e32 v9, v0
	v_mad_u32_u24 v5, v2, s33, v5
	v_add_u32_e32 v4, s27, v8
	v_add3_u32 v3, s27, v1, v3
	s_cselect_b64 s[0:1], -1, 0
	v_lshl_add_u64 v[6:7], s[2:3], 0, v[8:9]
	v_mov_b32_e32 v1, v2
	v_add3_u32 v5, v5, v8, 0
	v_lshlrev_b32_e32 v8, 1, v10
	v_lshlrev_b32_e32 v10, 1, v12
	v_lshlrev_b32_e32 v12, 1, v14
	v_lshlrev_b32_e32 v14, 1, v16
	v_lshlrev_b32_e32 v16, 1, v18
	s_branch .LBB0_686
